# baseline (speedup 1.0000x reference)
; __device__ __forceinline__ float sigmoidf_(float v) { return __builtin_amdgcn_rcpf(1.f + __expf(-v)); }
;     ...
;   } else {
;     u16* out = (u16*)outv + (size_t)(brow + wr * 64 + fr) * pitch + col0 + wc * 32 + (fq & 1) * 16 + (fq >> 1) * 8;
; #pragma unroll
;     for (int m = 0; m < 8; ++m)
; #pragma unroll
;       for (int np = 0; np < 2; ++np) {
;         unsigned pk[2][2];
; #pragma unroll
;         for (int h = 0; h < 2; ++h) {
;           float v[4];
; #pragma unroll
;           for (int j = 0; j < 4; ++j) {
;             v[j] = acc[m][2 * np + h][j];
;             v[j] = mode ? fmaxf(sigmoidf_(v[j]), 1e-18f) : v[j] * scale;
;           }
;           pk[h][0] = pack2(v[0], v[1]);
;           pk[h][1] = pack2(v[2], v[3]);
;         }
;         *(i32x4*)(out + (size_t)ROWOFF(m) * pitch + COLOFF(2 * np)) = widen_pair(pk[0][0], pk[0][1], pk[1][0], pk[1][1]);
;       }
;   }
.LBB0_170:
	s_or_b64 exec, exec, s[4:5]
	s_and_b64 vcc, exec, s[26:27]
	s_cbranch_vccnz .Lp1a_m1
	s_cmp_eq_u32 s0, 0
	v_cndmask_b32_e64 v128, 0, 1, s[26:27]
	s_cselect_b64 s[0:1], -1, 0
	v_mov_b32_e32 v129, v214
	v_cmp_ne_u32_e64 s[4:5], 1, v128
	s_andn2_b64 vcc, exec, s[26:27]
	s_mov_b64 s[26:27], -1
	s_andn2_b64 vcc, exec, s[26:27]
	v_cndmask_b32_e64 v128, 1.0, v204, s[0:1]
	v_mul_f32_e32 v130, v128, v124
	s_and_b64 vcc, exec, s[4:5]
	s_mov_b64 s[0:1], -1
	s_andn2_b64 vcc, exec, s[0:1]
	v_mul_f32_e32 v124, v128, v125
	s_and_b64 vcc, exec, s[4:5]
	s_mov_b64 s[0:1], -1
	s_andn2_b64 vcc, exec, s[0:1]
	v_mul_f32_e32 v125, v128, v126
	s_and_b64 vcc, exec, s[4:5]
	s_mov_b64 s[0:1], -1
	s_andn2_b64 vcc, exec, s[0:1]
	v_mul_f32_e32 v126, v128, v127
	s_and_b64 vcc, exec, s[4:5]
	s_mov_b64 s[0:1], -1
	s_andn2_b64 vcc, exec, s[0:1]
	v_mul_f32_e32 v127, v128, v120
	s_and_b64 vcc, exec, s[4:5]
	s_mov_b64 s[0:1], -1
	s_andn2_b64 vcc, exec, s[0:1]
	v_mul_f32_e32 v131, v128, v121
	s_and_b64 vcc, exec, s[4:5]
	s_mov_b64 s[0:1], -1
	s_andn2_b64 vcc, exec, s[0:1]
	v_mul_f32_e32 v132, v128, v122
	s_and_b64 vcc, exec, s[4:5]
	s_mov_b64 s[0:1], -1
	s_andn2_b64 vcc, exec, s[0:1]
	v_mul_f32_e32 v122, v128, v123
	v_ashrrev_i32_e32 v120, 2, v129
	v_and_b32_e32 v120, 0xffffffc0, v120
	v_and_or_b32 v121, v129, 15, s24
	v_add_u32_e32 v120, v121, v120
	v_ashrrev_i32_e32 v121, 31, v120
	s_and_b32 s0, s6, 0x700
	v_lshlrev_b64 v[120:121], 12, v[120:121]
	v_lshl_add_u64 v[120:121], s[22:23], 0, v[120:121]
	s_lshl_b32 s6, s0, 1
	v_cvt_pk_bf16_f32 v125, v125, v126
	v_lshl_add_u64 v[120:121], v[120:121], 0, s[6:7]
	v_and_b32_e32 v200, 0xc0, v129
	v_and_b32_e32 v126, 16, v129
	v_lshrrev_b32_e32 v123, 1, v129
	v_lshl_add_u64 v[120:121], v[120:121], 0, v[200:201]
	v_lshlrev_b32_e32 v200, 1, v126
	v_cvt_pk_bf16_f32 v124, v130, v124
	v_lshl_add_u64 v[120:121], v[120:121], 0, v[200:201]
	v_and_b32_e32 v200, 16, v123
	v_cvt_pk_bf16_f32 v126, v127, v131
	v_cvt_pk_bf16_f32 v127, v132, v122
	v_lshl_add_u64 v[120:121], v[120:121], 0, v[200:201]
	v_permlane16_swap_b32_e32 v124, v126
	v_permlane16_swap_b32_e32 v125, v127
	s_and_b64 vcc, exec, s[4:5]
	s_mov_b64 s[0:1], -1
	global_store_dwordx4 v[120:121], v[124:127], off
	s_andn2_b64 vcc, exec, s[0:1]
	v_mul_f32_e32 v122, v128, v116
	s_and_b64 vcc, exec, s[4:5]
	s_mov_b64 s[0:1], -1
	s_andn2_b64 vcc, exec, s[0:1]
	v_mul_f32_e32 v116, v128, v117
	s_and_b64 vcc, exec, s[4:5]
	s_mov_b64 s[0:1], -1
	s_andn2_b64 vcc, exec, s[0:1]
	v_mul_f32_e32 v117, v128, v118
	s_and_b64 vcc, exec, s[4:5]
	s_mov_b64 s[0:1], -1
	s_andn2_b64 vcc, exec, s[0:1]
	v_mul_f32_e32 v118, v128, v119
	s_and_b64 vcc, exec, s[4:5]
	s_mov_b64 s[0:1], -1
	s_andn2_b64 vcc, exec, s[0:1]
	v_mul_f32_e32 v119, v128, v112
	s_and_b64 vcc, exec, s[4:5]
	s_mov_b64 s[0:1], -1
	s_andn2_b64 vcc, exec, s[0:1]
	v_mul_f32_e32 v112, v128, v113
	s_and_b64 vcc, exec, s[4:5]
	s_mov_b64 s[0:1], -1
	s_andn2_b64 vcc, exec, s[0:1]
	v_mul_f32_e32 v113, v128, v114
	s_and_b64 vcc, exec, s[4:5]
	s_mov_b64 s[0:1], -1
	s_andn2_b64 vcc, exec, s[0:1]
	v_mul_f32_e32 v114, v128, v115
	v_cvt_pk_bf16_f32 v116, v122, v116
	v_cvt_pk_bf16_f32 v117, v117, v118
	v_cvt_pk_bf16_f32 v118, v119, v112
	v_cvt_pk_bf16_f32 v119, v113, v114
	s_nop 0
	v_permlane16_swap_b32_e32 v116, v118
	v_permlane16_swap_b32_e32 v117, v119
	s_and_b64 vcc, exec, s[4:5]
	s_mov_b64 s[0:1], -1
	global_store_dwordx4 v[120:121], v[116:119], off offset:256
	s_andn2_b64 vcc, exec, s[0:1]
	v_mul_f32_e32 v112, v128, v108
	s_and_b64 vcc, exec, s[4:5]
	s_mov_b64 s[0:1], -1
	s_andn2_b64 vcc, exec, s[0:1]
	v_mul_f32_e32 v108, v128, v109
	s_and_b64 vcc, exec, s[4:5]
	s_mov_b64 s[0:1], -1
	s_andn2_b64 vcc, exec, s[0:1]
	v_mul_f32_e32 v109, v128, v110
	s_and_b64 vcc, exec, s[4:5]
	s_mov_b64 s[0:1], -1
	s_andn2_b64 vcc, exec, s[0:1]
	v_mul_f32_e32 v110, v128, v111
	s_and_b64 vcc, exec, s[4:5]
	s_mov_b64 s[0:1], -1
	s_andn2_b64 vcc, exec, s[0:1]
	v_mul_f32_e32 v111, v128, v104
	s_and_b64 vcc, exec, s[4:5]
	s_mov_b64 s[0:1], -1
	s_andn2_b64 vcc, exec, s[0:1]
	v_mul_f32_e32 v104, v128, v105
	s_and_b64 vcc, exec, s[4:5]
	s_mov_b64 s[0:1], -1
	s_andn2_b64 vcc, exec, s[0:1]
	v_mul_f32_e32 v105, v128, v106
	s_and_b64 vcc, exec, s[4:5]
	s_mov_b64 s[0:1], -1
	s_andn2_b64 vcc, exec, s[0:1]
	v_mul_f32_e32 v106, v128, v107
	v_cvt_pk_bf16_f32 v109, v109, v110
	v_cvt_pk_bf16_f32 v110, v111, v104
	v_add_co_u32_e32 v104, vcc, 0x10000, v120
	v_cvt_pk_bf16_f32 v108, v112, v108
	v_cvt_pk_bf16_f32 v111, v105, v106
	v_addc_co_u32_e32 v105, vcc, 0, v121, vcc
	v_permlane16_swap_b32_e32 v108, v110
	v_permlane16_swap_b32_e32 v109, v111
	s_and_b64 vcc, exec, s[4:5]
	s_mov_b64 s[0:1], -1
	global_store_dwordx4 v[104:105], v[108:111], off
	s_andn2_b64 vcc, exec, s[0:1]
	v_mul_f32_e32 v104, v128, v100
	s_and_b64 vcc, exec, s[4:5]
	s_mov_b64 s[0:1], -1
	s_andn2_b64 vcc, exec, s[0:1]
	v_mul_f32_e32 v100, v128, v101
	s_and_b64 vcc, exec, s[4:5]
	s_mov_b64 s[0:1], -1
	s_andn2_b64 vcc, exec, s[0:1]
	v_mul_f32_e32 v101, v128, v102
	s_and_b64 vcc, exec, s[4:5]
	s_mov_b64 s[0:1], -1
	s_andn2_b64 vcc, exec, s[0:1]
	v_mul_f32_e32 v102, v128, v103
	s_and_b64 vcc, exec, s[4:5]
	s_mov_b64 s[0:1], -1
	s_andn2_b64 vcc, exec, s[0:1]
	v_mul_f32_e32 v103, v128, v96
	s_and_b64 vcc, exec, s[4:5]
	s_mov_b64 s[0:1], -1
	s_andn2_b64 vcc, exec, s[0:1]
	v_mul_f32_e32 v96, v128, v97
	s_and_b64 vcc, exec, s[4:5]
	s_mov_b64 s[0:1], -1
	s_andn2_b64 vcc, exec, s[0:1]
	v_mul_f32_e32 v97, v128, v98
	s_and_b64 vcc, exec, s[4:5]
	s_mov_b64 s[0:1], -1
	s_andn2_b64 vcc, exec, s[0:1]
	v_mul_f32_e32 v98, v128, v99
	v_cvt_pk_bf16_f32 v101, v101, v102
	v_cvt_pk_bf16_f32 v102, v103, v96
	v_add_co_u32_e32 v96, vcc, 0x10000, v120
; __device__ __forceinline__ float sigmoidf_(float v) { return __builtin_amdgcn_rcpf(1.f + __expf(-v)); }
;     ...
;   } else {
;     u16* out = (u16*)outv + (size_t)(brow + wr * 64 + fr) * pitch + col0 + wc * 32 + (fq & 1) * 16 + (fq >> 1) * 8;
; #pragma unroll
;     for (int m = 0; m < 8; ++m)
; #pragma unroll
;       for (int np = 0; np < 2; ++np) {
;         unsigned pk[2][2];
; #pragma unroll
;         for (int h = 0; h < 2; ++h) {
;           float v[4];
; #pragma unroll
;           for (int j = 0; j < 4; ++j) {
;             v[j] = acc[m][2 * np + h][j];
;             v[j] = mode ? fmaxf(sigmoidf_(v[j]), 1e-18f) : v[j] * scale;
;           }
;           pk[h][0] = pack2(v[0], v[1]);
;           pk[h][1] = pack2(v[2], v[3]);
;         }
;         *(i32x4*)(out + (size_t)ROWOFF(m) * pitch + COLOFF(2 * np)) = widen_pair(pk[0][0], pk[0][1], pk[1][0], pk[1][1]);
;       }
;   }
	v_cvt_pk_bf16_f32 v100, v104, v100
	v_cvt_pk_bf16_f32 v103, v97, v98
	v_addc_co_u32_e32 v97, vcc, 0, v121, vcc
	v_permlane16_swap_b32_e32 v100, v102
	v_permlane16_swap_b32_e32 v101, v103
	s_and_b64 vcc, exec, s[4:5]
	s_mov_b64 s[0:1], -1
	global_store_dwordx4 v[96:97], v[100:103], off offset:256
	s_andn2_b64 vcc, exec, s[0:1]
	v_mul_f32_e32 v96, v128, v92
	s_and_b64 vcc, exec, s[4:5]
	s_mov_b64 s[0:1], -1
	s_andn2_b64 vcc, exec, s[0:1]
	v_mul_f32_e32 v92, v128, v93
	s_and_b64 vcc, exec, s[4:5]
	s_mov_b64 s[0:1], -1
	s_andn2_b64 vcc, exec, s[0:1]
	v_mul_f32_e32 v93, v128, v94
	s_and_b64 vcc, exec, s[4:5]
	s_mov_b64 s[0:1], -1
	s_andn2_b64 vcc, exec, s[0:1]
	v_mul_f32_e32 v94, v128, v95
	s_and_b64 vcc, exec, s[4:5]
	s_mov_b64 s[0:1], -1
	s_andn2_b64 vcc, exec, s[0:1]
	v_mul_f32_e32 v95, v128, v88
	s_and_b64 vcc, exec, s[4:5]
	s_mov_b64 s[0:1], -1
	s_andn2_b64 vcc, exec, s[0:1]
	v_mul_f32_e32 v88, v128, v89
	s_and_b64 vcc, exec, s[4:5]
	s_mov_b64 s[0:1], -1
	s_andn2_b64 vcc, exec, s[0:1]
	v_mul_f32_e32 v89, v128, v90
	s_and_b64 vcc, exec, s[4:5]
	s_mov_b64 s[0:1], -1
	s_andn2_b64 vcc, exec, s[0:1]
	v_mul_f32_e32 v90, v128, v91
	v_cvt_pk_bf16_f32 v93, v93, v94
	v_cvt_pk_bf16_f32 v94, v95, v88
	v_add_co_u32_e32 v88, vcc, 0x20000, v120
	v_cvt_pk_bf16_f32 v92, v96, v92
	v_cvt_pk_bf16_f32 v95, v89, v90
	v_addc_co_u32_e32 v89, vcc, 0, v121, vcc
	v_permlane16_swap_b32_e32 v92, v94
	v_permlane16_swap_b32_e32 v93, v95
	s_and_b64 vcc, exec, s[4:5]
	s_mov_b64 s[0:1], -1
	global_store_dwordx4 v[88:89], v[92:95], off
	s_andn2_b64 vcc, exec, s[0:1]
	v_mul_f32_e32 v88, v128, v84
	s_and_b64 vcc, exec, s[4:5]
	s_mov_b64 s[0:1], -1
	s_andn2_b64 vcc, exec, s[0:1]
	v_mul_f32_e32 v84, v128, v85
	s_and_b64 vcc, exec, s[4:5]
	s_mov_b64 s[0:1], -1
	s_andn2_b64 vcc, exec, s[0:1]
	v_mul_f32_e32 v85, v128, v86
	s_and_b64 vcc, exec, s[4:5]
	s_mov_b64 s[0:1], -1
	s_andn2_b64 vcc, exec, s[0:1]
	v_mul_f32_e32 v86, v128, v87
	s_and_b64 vcc, exec, s[4:5]
	s_mov_b64 s[0:1], -1
	s_andn2_b64 vcc, exec, s[0:1]
	v_mul_f32_e32 v87, v128, v80
	s_and_b64 vcc, exec, s[4:5]
	s_mov_b64 s[0:1], -1
	s_andn2_b64 vcc, exec, s[0:1]
	v_mul_f32_e32 v80, v128, v81
	s_and_b64 vcc, exec, s[4:5]
	s_mov_b64 s[0:1], -1
	s_andn2_b64 vcc, exec, s[0:1]
	v_mul_f32_e32 v81, v128, v82
	s_and_b64 vcc, exec, s[4:5]
	s_mov_b64 s[0:1], -1
	s_andn2_b64 vcc, exec, s[0:1]
	v_mul_f32_e32 v82, v128, v83
	v_cvt_pk_bf16_f32 v85, v85, v86
	v_cvt_pk_bf16_f32 v86, v87, v80
	v_add_co_u32_e32 v80, vcc, 0x20000, v120
	v_cvt_pk_bf16_f32 v84, v88, v84
	v_cvt_pk_bf16_f32 v87, v81, v82
	v_addc_co_u32_e32 v81, vcc, 0, v121, vcc
	v_permlane16_swap_b32_e32 v84, v86
	v_permlane16_swap_b32_e32 v85, v87
	s_and_b64 vcc, exec, s[4:5]
	s_mov_b64 s[0:1], -1
	global_store_dwordx4 v[80:81], v[84:87], off offset:256
	s_andn2_b64 vcc, exec, s[0:1]
	v_mul_f32_e32 v80, v128, v76
	s_and_b64 vcc, exec, s[4:5]
	s_mov_b64 s[0:1], -1
	s_andn2_b64 vcc, exec, s[0:1]
	v_mul_f32_e32 v76, v128, v77
	s_and_b64 vcc, exec, s[4:5]
	s_mov_b64 s[0:1], -1
	s_andn2_b64 vcc, exec, s[0:1]
	v_mul_f32_e32 v77, v128, v78
	s_and_b64 vcc, exec, s[4:5]
	s_mov_b64 s[0:1], -1
	s_andn2_b64 vcc, exec, s[0:1]
	v_mul_f32_e32 v78, v128, v79
	s_and_b64 vcc, exec, s[4:5]
	s_mov_b64 s[0:1], -1
	s_andn2_b64 vcc, exec, s[0:1]
	v_mul_f32_e32 v79, v128, v72
	s_and_b64 vcc, exec, s[4:5]
	s_mov_b64 s[0:1], -1
	s_andn2_b64 vcc, exec, s[0:1]
	v_mul_f32_e32 v72, v128, v73
	s_and_b64 vcc, exec, s[4:5]
	s_mov_b64 s[0:1], -1
	s_andn2_b64 vcc, exec, s[0:1]
	v_mul_f32_e32 v73, v128, v74
	s_and_b64 vcc, exec, s[4:5]
	s_mov_b64 s[0:1], -1
	s_andn2_b64 vcc, exec, s[0:1]
	v_mul_f32_e32 v74, v128, v75
	v_cvt_pk_bf16_f32 v77, v77, v78
	v_cvt_pk_bf16_f32 v78, v79, v72
	v_add_co_u32_e32 v72, vcc, 0x30000, v120
	v_cvt_pk_bf16_f32 v76, v80, v76
	v_cvt_pk_bf16_f32 v79, v73, v74
	v_addc_co_u32_e32 v73, vcc, 0, v121, vcc
	v_permlane16_swap_b32_e32 v76, v78
	v_permlane16_swap_b32_e32 v77, v79
	s_and_b64 vcc, exec, s[4:5]
	s_mov_b64 s[0:1], -1
	global_store_dwordx4 v[72:73], v[76:79], off
	s_andn2_b64 vcc, exec, s[0:1]
	v_mul_f32_e32 v72, v128, v68
	s_and_b64 vcc, exec, s[4:5]
	s_mov_b64 s[0:1], -1
	s_andn2_b64 vcc, exec, s[0:1]
	v_mul_f32_e32 v68, v128, v69
	s_and_b64 vcc, exec, s[4:5]
	s_mov_b64 s[0:1], -1
	s_andn2_b64 vcc, exec, s[0:1]
	v_mul_f32_e32 v69, v128, v70
	s_and_b64 vcc, exec, s[4:5]
	s_mov_b64 s[0:1], -1
	s_andn2_b64 vcc, exec, s[0:1]
	v_mul_f32_e32 v70, v128, v71
	s_and_b64 vcc, exec, s[4:5]
	s_mov_b64 s[0:1], -1
	s_andn2_b64 vcc, exec, s[0:1]
	v_mul_f32_e32 v71, v128, v64
	s_and_b64 vcc, exec, s[4:5]
	s_mov_b64 s[0:1], -1
	s_andn2_b64 vcc, exec, s[0:1]
	v_mul_f32_e32 v64, v128, v65
	s_and_b64 vcc, exec, s[4:5]
	s_mov_b64 s[0:1], -1
	s_andn2_b64 vcc, exec, s[0:1]
	v_mul_f32_e32 v65, v128, v66
	s_and_b64 vcc, exec, s[4:5]
	s_mov_b64 s[0:1], -1
	s_andn2_b64 vcc, exec, s[0:1]
	v_mul_f32_e32 v66, v128, v67
	v_cvt_pk_bf16_f32 v69, v69, v70
	v_cvt_pk_bf16_f32 v70, v71, v64
	v_add_co_u32_e32 v64, vcc, 0x30000, v120
	v_cvt_pk_bf16_f32 v68, v72, v68
	v_cvt_pk_bf16_f32 v71, v65, v66
	v_addc_co_u32_e32 v65, vcc, 0, v121, vcc
	v_permlane16_swap_b32_e32 v68, v70
	v_permlane16_swap_b32_e32 v69, v71
	s_and_b64 vcc, exec, s[4:5]
	s_mov_b64 s[0:1], -1
	global_store_dwordx4 v[64:65], v[68:71], off offset:256
	s_andn2_b64 vcc, exec, s[0:1]
	v_mul_f32_e32 v64, v128, v60
	s_and_b64 vcc, exec, s[4:5]
	s_mov_b64 s[0:1], -1
	s_andn2_b64 vcc, exec, s[0:1]
	v_mul_f32_e32 v60, v128, v61
	s_and_b64 vcc, exec, s[4:5]
	s_mov_b64 s[0:1], -1
	s_andn2_b64 vcc, exec, s[0:1]
	v_mul_f32_e32 v61, v128, v62
	s_and_b64 vcc, exec, s[4:5]
	s_mov_b64 s[0:1], -1
	s_andn2_b64 vcc, exec, s[0:1]
	v_mul_f32_e32 v62, v128, v63
; __device__ __forceinline__ float sigmoidf_(float v) { return __builtin_amdgcn_rcpf(1.f + __expf(-v)); }
;     ...
;   } else {
;     u16* out = (u16*)outv + (size_t)(brow + wr * 64 + fr) * pitch + col0 + wc * 32 + (fq & 1) * 16 + (fq >> 1) * 8;
; #pragma unroll
;     for (int m = 0; m < 8; ++m)
; #pragma unroll
;       for (int np = 0; np < 2; ++np) {
;         unsigned pk[2][2];
; #pragma unroll
;         for (int h = 0; h < 2; ++h) {
;           float v[4];
; #pragma unroll
;           for (int j = 0; j < 4; ++j) {
;             v[j] = acc[m][2 * np + h][j];
;             v[j] = mode ? fmaxf(sigmoidf_(v[j]), 1e-18f) : v[j] * scale;
;           }
;           pk[h][0] = pack2(v[0], v[1]);
;           pk[h][1] = pack2(v[2], v[3]);
;         }
;         *(i32x4*)(out + (size_t)ROWOFF(m) * pitch + COLOFF(2 * np)) = widen_pair(pk[0][0], pk[0][1], pk[1][0], pk[1][1]);
;       }
;   }
	s_and_b64 vcc, exec, s[4:5]
	s_mov_b64 s[0:1], -1
	s_andn2_b64 vcc, exec, s[0:1]
	v_mul_f32_e32 v63, v128, v56
	s_and_b64 vcc, exec, s[4:5]
	s_mov_b64 s[0:1], -1
	s_andn2_b64 vcc, exec, s[0:1]
	v_mul_f32_e32 v56, v128, v57
	s_and_b64 vcc, exec, s[4:5]
	s_mov_b64 s[0:1], -1
	s_andn2_b64 vcc, exec, s[0:1]
	v_mul_f32_e32 v57, v128, v58
	s_and_b64 vcc, exec, s[4:5]
	s_mov_b64 s[0:1], -1
	s_andn2_b64 vcc, exec, s[0:1]
	v_mul_f32_e32 v58, v128, v59
	v_cvt_pk_bf16_f32 v61, v61, v62
	v_cvt_pk_bf16_f32 v62, v63, v56
	v_add_co_u32_e32 v56, vcc, 0x80000, v120
	v_cvt_pk_bf16_f32 v60, v64, v60
	v_cvt_pk_bf16_f32 v63, v57, v58
	v_addc_co_u32_e32 v57, vcc, 0, v121, vcc
	v_permlane16_swap_b32_e32 v60, v62
	v_permlane16_swap_b32_e32 v61, v63
	s_and_b64 vcc, exec, s[4:5]
	s_mov_b64 s[0:1], -1
	global_store_dwordx4 v[56:57], v[60:63], off
	s_andn2_b64 vcc, exec, s[0:1]
	v_mul_f32_e32 v56, v128, v52
	s_and_b64 vcc, exec, s[4:5]
	s_mov_b64 s[0:1], -1
	s_andn2_b64 vcc, exec, s[0:1]
	v_mul_f32_e32 v52, v128, v53
	s_and_b64 vcc, exec, s[4:5]
	s_mov_b64 s[0:1], -1
	s_andn2_b64 vcc, exec, s[0:1]
	v_mul_f32_e32 v53, v128, v54
	s_and_b64 vcc, exec, s[4:5]
	s_mov_b64 s[0:1], -1
	s_andn2_b64 vcc, exec, s[0:1]
	v_mul_f32_e32 v54, v128, v55
	s_and_b64 vcc, exec, s[4:5]
	s_mov_b64 s[0:1], -1
	s_andn2_b64 vcc, exec, s[0:1]
	v_mul_f32_e32 v55, v128, v48
	s_and_b64 vcc, exec, s[4:5]
	s_mov_b64 s[0:1], -1
	s_andn2_b64 vcc, exec, s[0:1]
	v_mul_f32_e32 v48, v128, v49
	s_and_b64 vcc, exec, s[4:5]
	s_mov_b64 s[0:1], -1
	s_andn2_b64 vcc, exec, s[0:1]
	v_mul_f32_e32 v49, v128, v50
	s_and_b64 vcc, exec, s[4:5]
	s_mov_b64 s[0:1], -1
	s_andn2_b64 vcc, exec, s[0:1]
	v_mul_f32_e32 v50, v128, v51
	v_cvt_pk_bf16_f32 v53, v53, v54
	v_cvt_pk_bf16_f32 v54, v55, v48
	v_add_co_u32_e32 v48, vcc, 0x80000, v120
	v_cvt_pk_bf16_f32 v52, v56, v52
	v_cvt_pk_bf16_f32 v55, v49, v50
	v_addc_co_u32_e32 v49, vcc, 0, v121, vcc
	v_permlane16_swap_b32_e32 v52, v54
	v_permlane16_swap_b32_e32 v53, v55
	s_and_b64 vcc, exec, s[4:5]
	s_mov_b64 s[0:1], -1
	global_store_dwordx4 v[48:49], v[52:55], off offset:256
	s_andn2_b64 vcc, exec, s[0:1]
	v_mul_f32_e32 v48, v128, v44
	s_and_b64 vcc, exec, s[4:5]
	s_mov_b64 s[0:1], -1
	s_andn2_b64 vcc, exec, s[0:1]
	v_mul_f32_e32 v44, v128, v45
	s_and_b64 vcc, exec, s[4:5]
	s_mov_b64 s[0:1], -1
	s_andn2_b64 vcc, exec, s[0:1]
	v_mul_f32_e32 v45, v128, v46
	s_and_b64 vcc, exec, s[4:5]
	s_mov_b64 s[0:1], -1
	s_andn2_b64 vcc, exec, s[0:1]
	v_mul_f32_e32 v46, v128, v47
	s_and_b64 vcc, exec, s[4:5]
	s_mov_b64 s[0:1], -1
	s_andn2_b64 vcc, exec, s[0:1]
	v_mul_f32_e32 v47, v128, v40
	s_and_b64 vcc, exec, s[4:5]
	s_mov_b64 s[0:1], -1
	s_andn2_b64 vcc, exec, s[0:1]
	v_mul_f32_e32 v40, v128, v41
	s_and_b64 vcc, exec, s[4:5]
	s_mov_b64 s[0:1], -1
	s_andn2_b64 vcc, exec, s[0:1]
	v_mul_f32_e32 v41, v128, v42
	s_and_b64 vcc, exec, s[4:5]
	s_mov_b64 s[0:1], -1
	s_andn2_b64 vcc, exec, s[0:1]
	v_mul_f32_e32 v42, v128, v43
	v_cvt_pk_bf16_f32 v45, v45, v46
	v_cvt_pk_bf16_f32 v46, v47, v40
	v_add_co_u32_e32 v40, vcc, 0x90000, v120
	v_cvt_pk_bf16_f32 v44, v48, v44
	v_cvt_pk_bf16_f32 v47, v41, v42
	v_addc_co_u32_e32 v41, vcc, 0, v121, vcc
	v_permlane16_swap_b32_e32 v44, v46
	v_permlane16_swap_b32_e32 v45, v47
	s_and_b64 vcc, exec, s[4:5]
	s_mov_b64 s[0:1], -1
	global_store_dwordx4 v[40:41], v[44:47], off
	s_andn2_b64 vcc, exec, s[0:1]
	v_mul_f32_e32 v40, v128, v36
	s_and_b64 vcc, exec, s[4:5]
	s_mov_b64 s[0:1], -1
	s_andn2_b64 vcc, exec, s[0:1]
	v_mul_f32_e32 v36, v128, v37
	s_and_b64 vcc, exec, s[4:5]
	s_mov_b64 s[0:1], -1
	s_andn2_b64 vcc, exec, s[0:1]
	v_mul_f32_e32 v37, v128, v38
	s_and_b64 vcc, exec, s[4:5]
	s_mov_b64 s[0:1], -1
	s_andn2_b64 vcc, exec, s[0:1]
	v_mul_f32_e32 v38, v128, v39
	s_and_b64 vcc, exec, s[4:5]
	s_mov_b64 s[0:1], -1
	s_andn2_b64 vcc, exec, s[0:1]
	v_mul_f32_e32 v39, v128, v32
	s_and_b64 vcc, exec, s[4:5]
	s_mov_b64 s[0:1], -1
	s_andn2_b64 vcc, exec, s[0:1]
	v_mul_f32_e32 v32, v128, v33
	s_and_b64 vcc, exec, s[4:5]
	s_mov_b64 s[0:1], -1
	s_andn2_b64 vcc, exec, s[0:1]
	v_mul_f32_e32 v33, v128, v34
	s_and_b64 vcc, exec, s[4:5]
	s_mov_b64 s[0:1], -1
	s_andn2_b64 vcc, exec, s[0:1]
	v_mul_f32_e32 v34, v128, v35
	v_cvt_pk_bf16_f32 v37, v37, v38
	v_cvt_pk_bf16_f32 v38, v39, v32
	v_add_co_u32_e32 v32, vcc, 0x90000, v120
	v_cvt_pk_bf16_f32 v36, v40, v36
	v_cvt_pk_bf16_f32 v39, v33, v34
	v_addc_co_u32_e32 v33, vcc, 0, v121, vcc
	v_permlane16_swap_b32_e32 v36, v38
	v_permlane16_swap_b32_e32 v37, v39
	s_and_b64 vcc, exec, s[4:5]
	s_mov_b64 s[0:1], -1
	global_store_dwordx4 v[32:33], v[36:39], off offset:256
	s_andn2_b64 vcc, exec, s[0:1]
	v_mul_f32_e32 v32, v128, v28
	s_and_b64 vcc, exec, s[4:5]
	s_mov_b64 s[0:1], -1
	s_andn2_b64 vcc, exec, s[0:1]
	v_mul_f32_e32 v28, v128, v29
	s_and_b64 vcc, exec, s[4:5]
	s_mov_b64 s[0:1], -1
	s_andn2_b64 vcc, exec, s[0:1]
	v_mul_f32_e32 v29, v128, v30
	s_and_b64 vcc, exec, s[4:5]
	s_mov_b64 s[0:1], -1
	s_andn2_b64 vcc, exec, s[0:1]
	v_mul_f32_e32 v30, v128, v31
	s_and_b64 vcc, exec, s[4:5]
	s_mov_b64 s[0:1], -1
	s_andn2_b64 vcc, exec, s[0:1]
	v_mul_f32_e32 v31, v128, v24
	s_and_b64 vcc, exec, s[4:5]
	s_mov_b64 s[0:1], -1
	s_andn2_b64 vcc, exec, s[0:1]
	v_mul_f32_e32 v24, v128, v25
	s_and_b64 vcc, exec, s[4:5]
	s_mov_b64 s[0:1], -1
	s_andn2_b64 vcc, exec, s[0:1]
	v_mul_f32_e32 v25, v128, v26
	s_and_b64 vcc, exec, s[4:5]
	s_mov_b64 s[0:1], -1
	s_andn2_b64 vcc, exec, s[0:1]
	v_mul_f32_e32 v26, v128, v27
	v_cvt_pk_bf16_f32 v29, v29, v30
	v_cvt_pk_bf16_f32 v30, v31, v24
	v_add_co_u32_e32 v24, vcc, 0xa0000, v120
	v_cvt_pk_bf16_f32 v28, v32, v28
	v_cvt_pk_bf16_f32 v31, v25, v26
	v_addc_co_u32_e32 v25, vcc, 0, v121, vcc
	v_permlane16_swap_b32_e32 v28, v30
; __device__ __forceinline__ float sigmoidf_(float v) { return __builtin_amdgcn_rcpf(1.f + __expf(-v)); }
;     ...
;   } else {
;     u16* out = (u16*)outv + (size_t)(brow + wr * 64 + fr) * pitch + col0 + wc * 32 + (fq & 1) * 16 + (fq >> 1) * 8;
; #pragma unroll
;     for (int m = 0; m < 8; ++m)
; #pragma unroll
;       for (int np = 0; np < 2; ++np) {
;         unsigned pk[2][2];
; #pragma unroll
;         for (int h = 0; h < 2; ++h) {
;           float v[4];
; #pragma unroll
;           for (int j = 0; j < 4; ++j) {
;             v[j] = acc[m][2 * np + h][j];
;             v[j] = mode ? fmaxf(sigmoidf_(v[j]), 1e-18f) : v[j] * scale;
;           }
;           pk[h][0] = pack2(v[0], v[1]);
;           pk[h][1] = pack2(v[2], v[3]);
;         }
;         *(i32x4*)(out + (size_t)ROWOFF(m) * pitch + COLOFF(2 * np)) = widen_pair(pk[0][0], pk[0][1], pk[1][0], pk[1][1]);
;       }
;   }
	v_permlane16_swap_b32_e32 v29, v31
	s_and_b64 vcc, exec, s[4:5]
	s_mov_b64 s[0:1], -1
	global_store_dwordx4 v[24:25], v[28:31], off
	s_andn2_b64 vcc, exec, s[0:1]
	v_mul_f32_e32 v24, v128, v20
	s_and_b64 vcc, exec, s[4:5]
	s_mov_b64 s[0:1], -1
	s_andn2_b64 vcc, exec, s[0:1]
	v_mul_f32_e32 v20, v128, v21
	s_and_b64 vcc, exec, s[4:5]
	s_mov_b64 s[0:1], -1
	s_andn2_b64 vcc, exec, s[0:1]
	v_mul_f32_e32 v21, v128, v22
	s_and_b64 vcc, exec, s[4:5]
	s_mov_b64 s[0:1], -1
	s_andn2_b64 vcc, exec, s[0:1]
	v_mul_f32_e32 v22, v128, v23
	s_and_b64 vcc, exec, s[4:5]
	s_mov_b64 s[0:1], -1
	s_andn2_b64 vcc, exec, s[0:1]
	v_mul_f32_e32 v23, v128, v16
	s_and_b64 vcc, exec, s[4:5]
	s_mov_b64 s[0:1], -1
	s_andn2_b64 vcc, exec, s[0:1]
	v_mul_f32_e32 v16, v128, v17
	s_and_b64 vcc, exec, s[4:5]
	s_mov_b64 s[0:1], -1
	s_andn2_b64 vcc, exec, s[0:1]
	v_mul_f32_e32 v17, v128, v18
	s_and_b64 vcc, exec, s[4:5]
	s_mov_b64 s[0:1], -1
	s_andn2_b64 vcc, exec, s[0:1]
	v_mul_f32_e32 v18, v128, v19
	v_cvt_pk_bf16_f32 v21, v21, v22
	v_cvt_pk_bf16_f32 v22, v23, v16
	v_add_co_u32_e32 v16, vcc, 0xa0000, v120
	v_cvt_pk_bf16_f32 v20, v24, v20
	v_cvt_pk_bf16_f32 v23, v17, v18
	v_addc_co_u32_e32 v17, vcc, 0, v121, vcc
	v_permlane16_swap_b32_e32 v20, v22
	v_permlane16_swap_b32_e32 v21, v23
	s_and_b64 vcc, exec, s[4:5]
	s_mov_b64 s[0:1], -1
	global_store_dwordx4 v[16:17], v[20:23], off offset:256
	s_andn2_b64 vcc, exec, s[0:1]
	v_mul_f32_e32 v16, v128, v12
	s_and_b64 vcc, exec, s[4:5]
	s_mov_b64 s[0:1], -1
	s_andn2_b64 vcc, exec, s[0:1]
	v_mul_f32_e32 v12, v128, v13
	s_and_b64 vcc, exec, s[4:5]
	s_mov_b64 s[0:1], -1
	s_andn2_b64 vcc, exec, s[0:1]
	v_mul_f32_e32 v13, v128, v14
	s_and_b64 vcc, exec, s[4:5]
	s_mov_b64 s[0:1], -1
	s_andn2_b64 vcc, exec, s[0:1]
	v_mul_f32_e32 v14, v128, v15
	s_and_b64 vcc, exec, s[4:5]
	s_mov_b64 s[0:1], -1
	s_andn2_b64 vcc, exec, s[0:1]
	v_mul_f32_e32 v15, v128, v8
	s_and_b64 vcc, exec, s[4:5]
	s_mov_b64 s[0:1], -1
	s_andn2_b64 vcc, exec, s[0:1]
	v_mul_f32_e32 v8, v128, v9
	s_and_b64 vcc, exec, s[4:5]
	s_mov_b64 s[0:1], -1
	s_andn2_b64 vcc, exec, s[0:1]
	v_mul_f32_e32 v9, v128, v10
	s_and_b64 vcc, exec, s[4:5]
	s_mov_b64 s[0:1], -1
	s_andn2_b64 vcc, exec, s[0:1]
	v_mul_f32_e32 v10, v128, v11
	v_cvt_pk_bf16_f32 v13, v13, v14
	v_cvt_pk_bf16_f32 v14, v15, v8
	v_add_co_u32_e32 v8, vcc, 0xb0000, v120
	v_cvt_pk_bf16_f32 v12, v16, v12
	v_cvt_pk_bf16_f32 v15, v9, v10
	v_addc_co_u32_e32 v9, vcc, 0, v121, vcc
	v_permlane16_swap_b32_e32 v12, v14
	v_permlane16_swap_b32_e32 v13, v15
	s_and_b64 vcc, exec, s[4:5]
	s_mov_b64 s[0:1], -1
	global_store_dwordx4 v[8:9], v[12:15], off
	s_andn2_b64 vcc, exec, s[0:1]
	v_mul_f32_e32 v8, v128, v4
	s_and_b64 vcc, exec, s[4:5]
	s_mov_b64 s[0:1], -1
	s_andn2_b64 vcc, exec, s[0:1]
	v_mul_f32_e32 v4, v128, v5
	s_and_b64 vcc, exec, s[4:5]
	s_mov_b64 s[0:1], -1
	s_andn2_b64 vcc, exec, s[0:1]
	v_mul_f32_e32 v5, v128, v6
	s_and_b64 vcc, exec, s[4:5]
	s_mov_b64 s[0:1], -1
	s_andn2_b64 vcc, exec, s[0:1]
	v_mul_f32_e32 v6, v128, v7
	s_and_b64 vcc, exec, s[4:5]
	s_mov_b64 s[0:1], -1
	s_andn2_b64 vcc, exec, s[0:1]
	v_mul_f32_e32 v7, v128, v0
	s_and_b64 vcc, exec, s[4:5]
	s_mov_b64 s[0:1], -1
	s_andn2_b64 vcc, exec, s[0:1]
	v_mul_f32_e32 v0, v128, v1
	s_and_b64 vcc, exec, s[4:5]
	s_mov_b64 s[0:1], -1
	s_andn2_b64 vcc, exec, s[0:1]
	v_mul_f32_e32 v1, v128, v2
	s_and_b64 vcc, exec, s[4:5]
	s_mov_b64 s[0:1], -1
	s_andn2_b64 vcc, exec, s[0:1]
	v_mul_f32_e32 v2, v128, v3
	s_branch .LBB0_143
.Lp1a_m1:
	s_cmp_eq_u32 s0, 0
	v_cndmask_b32_e64 v128, 0, 1, s[26:27]
	s_cselect_b64 s[0:1], -1, 0
	v_mov_b32_e32 v129, v214
	v_cmp_ne_u32_e64 s[4:5], 1, v128
	s_andn2_b64 vcc, exec, s[26:27]
	s_mov_b64 s[26:27], -1
	v_mul_f32_e32 v128, 0xbfb8aa3b, v124
	v_exp_f32_e32 v128, v128
	s_nop 0
	v_add_f32_e32 v128, 1.0, v128
	v_rcp_f32_e32 v128, v128
	s_nop 0
	v_max_f32_e32 v130, 0x219392ef, v128
	v_cndmask_b32_e64 v128, 1.0, v204, s[0:1]
	s_and_b64 vcc, exec, s[4:5]
	s_mov_b64 s[0:1], -1
	v_mul_f32_e32 v124, 0xbfb8aa3b, v125
	v_exp_f32_e32 v124, v124
	s_nop 0
	v_add_f32_e32 v124, 1.0, v124
	v_rcp_f32_e32 v124, v124
	s_nop 0
	v_max_f32_e32 v124, 0x219392ef, v124
	s_and_b64 vcc, exec, s[4:5]
	s_mov_b64 s[0:1], -1
	v_mul_f32_e32 v125, 0xbfb8aa3b, v126
	v_exp_f32_e32 v125, v125
	s_nop 0
	v_add_f32_e32 v125, 1.0, v125
	v_rcp_f32_e32 v125, v125
	s_nop 0
	v_max_f32_e32 v125, 0x219392ef, v125
	s_and_b64 vcc, exec, s[4:5]
	s_mov_b64 s[0:1], -1
	v_mul_f32_e32 v126, 0xbfb8aa3b, v127
	v_exp_f32_e32 v126, v126
	s_nop 0
	v_add_f32_e32 v126, 1.0, v126
	v_rcp_f32_e32 v126, v126
	s_nop 0
	v_max_f32_e32 v126, 0x219392ef, v126
	s_and_b64 vcc, exec, s[4:5]
	s_mov_b64 s[0:1], -1
	v_mul_f32_e32 v127, 0xbfb8aa3b, v120
	v_exp_f32_e32 v127, v127
	s_nop 0
	v_add_f32_e32 v127, 1.0, v127
	v_rcp_f32_e32 v127, v127
	s_nop 0
	v_max_f32_e32 v127, 0x219392ef, v127
	s_and_b64 vcc, exec, s[4:5]
	s_mov_b64 s[0:1], -1
	v_mul_f32_e32 v120, 0xbfb8aa3b, v121
	v_exp_f32_e32 v120, v120
	s_nop 0
	v_add_f32_e32 v120, 1.0, v120
	v_rcp_f32_e32 v120, v120
	s_nop 0
	v_max_f32_e32 v131, 0x219392ef, v120
	s_and_b64 vcc, exec, s[4:5]
	s_mov_b64 s[0:1], -1
	v_mul_f32_e32 v120, 0xbfb8aa3b, v122
	v_exp_f32_e32 v120, v120
	s_nop 0
	v_add_f32_e32 v120, 1.0, v120
	v_rcp_f32_e32 v120, v120
	s_nop 0
	v_max_f32_e32 v132, 0x219392ef, v120
	s_and_b64 vcc, exec, s[4:5]
	s_mov_b64 s[0:1], -1
	v_mul_f32_e32 v120, 0xbfb8aa3b, v123
	v_exp_f32_e32 v120, v120
	s_nop 0
	v_add_f32_e32 v120, 1.0, v120
	v_rcp_f32_e32 v120, v120
	s_nop 0
	v_max_f32_e32 v122, 0x219392ef, v120
	v_ashrrev_i32_e32 v120, 2, v129
	v_and_b32_e32 v120, 0xffffffc0, v120
	v_and_or_b32 v121, v129, 15, s24
	v_add_u32_e32 v120, v121, v120
	v_ashrrev_i32_e32 v121, 31, v120
; __device__ __forceinline__ float sigmoidf_(float v) { return __builtin_amdgcn_rcpf(1.f + __expf(-v)); }
;     ...
;   } else {
;     u16* out = (u16*)outv + (size_t)(brow + wr * 64 + fr) * pitch + col0 + wc * 32 + (fq & 1) * 16 + (fq >> 1) * 8;
; #pragma unroll
;     for (int m = 0; m < 8; ++m)
; #pragma unroll
;       for (int np = 0; np < 2; ++np) {
;         unsigned pk[2][2];
; #pragma unroll
;         for (int h = 0; h < 2; ++h) {
;           float v[4];
; #pragma unroll
;           for (int j = 0; j < 4; ++j) {
;             v[j] = acc[m][2 * np + h][j];
;             v[j] = mode ? fmaxf(sigmoidf_(v[j]), 1e-18f) : v[j] * scale;
;           }
;           pk[h][0] = pack2(v[0], v[1]);
;           pk[h][1] = pack2(v[2], v[3]);
;         }
;         *(i32x4*)(out + (size_t)ROWOFF(m) * pitch + COLOFF(2 * np)) = widen_pair(pk[0][0], pk[0][1], pk[1][0], pk[1][1]);
;       }
;   }
	s_and_b32 s0, s6, 0x700
	v_lshlrev_b64 v[120:121], 12, v[120:121]
	v_lshl_add_u64 v[120:121], s[22:23], 0, v[120:121]
	s_lshl_b32 s6, s0, 1
	v_cvt_pk_bf16_f32 v125, v125, v126
	v_lshl_add_u64 v[120:121], v[120:121], 0, s[6:7]
	v_and_b32_e32 v200, 0xc0, v129
	v_and_b32_e32 v126, 16, v129
	v_lshrrev_b32_e32 v123, 1, v129
	v_lshl_add_u64 v[120:121], v[120:121], 0, v[200:201]
	v_lshlrev_b32_e32 v200, 1, v126
	v_cvt_pk_bf16_f32 v124, v130, v124
	v_lshl_add_u64 v[120:121], v[120:121], 0, v[200:201]
	v_and_b32_e32 v200, 16, v123
	v_cvt_pk_bf16_f32 v126, v127, v131
	v_cvt_pk_bf16_f32 v127, v132, v122
	v_lshl_add_u64 v[120:121], v[120:121], 0, v[200:201]
	v_permlane16_swap_b32_e32 v124, v126
	v_permlane16_swap_b32_e32 v125, v127
	s_and_b64 vcc, exec, s[4:5]
	s_mov_b64 s[0:1], -1
	global_store_dwordx4 v[120:121], v[124:127], off
	v_mul_f32_e32 v122, 0xbfb8aa3b, v116
	v_exp_f32_e32 v122, v122
	s_nop 0
	v_add_f32_e32 v122, 1.0, v122
	v_rcp_f32_e32 v122, v122
	s_nop 0
	v_max_f32_e32 v122, 0x219392ef, v122
	s_and_b64 vcc, exec, s[4:5]
	s_mov_b64 s[0:1], -1
	v_mul_f32_e32 v116, 0xbfb8aa3b, v117
	v_exp_f32_e32 v116, v116
	s_nop 0
	v_add_f32_e32 v116, 1.0, v116
	v_rcp_f32_e32 v116, v116
	s_nop 0
	v_max_f32_e32 v116, 0x219392ef, v116
	s_and_b64 vcc, exec, s[4:5]
	s_mov_b64 s[0:1], -1
	v_mul_f32_e32 v117, 0xbfb8aa3b, v118
	v_exp_f32_e32 v117, v117
	s_nop 0
	v_add_f32_e32 v117, 1.0, v117
	v_rcp_f32_e32 v117, v117
	s_nop 0
	v_max_f32_e32 v117, 0x219392ef, v117
	s_and_b64 vcc, exec, s[4:5]
	s_mov_b64 s[0:1], -1
	v_mul_f32_e32 v118, 0xbfb8aa3b, v119
	v_exp_f32_e32 v118, v118
	s_nop 0
	v_add_f32_e32 v118, 1.0, v118
	v_rcp_f32_e32 v118, v118
	s_nop 0
	v_max_f32_e32 v118, 0x219392ef, v118
	s_and_b64 vcc, exec, s[4:5]
	s_mov_b64 s[0:1], -1
	v_mul_f32_e32 v119, 0xbfb8aa3b, v112
	v_exp_f32_e32 v119, v119
	s_nop 0
	v_add_f32_e32 v119, 1.0, v119
	v_rcp_f32_e32 v119, v119
	s_nop 0
	v_max_f32_e32 v119, 0x219392ef, v119
	s_and_b64 vcc, exec, s[4:5]
	s_mov_b64 s[0:1], -1
	v_mul_f32_e32 v112, 0xbfb8aa3b, v113
	v_exp_f32_e32 v112, v112
	s_nop 0
	v_add_f32_e32 v112, 1.0, v112
	v_rcp_f32_e32 v112, v112
	s_nop 0
	v_max_f32_e32 v112, 0x219392ef, v112
	s_and_b64 vcc, exec, s[4:5]
	s_mov_b64 s[0:1], -1
	v_mul_f32_e32 v113, 0xbfb8aa3b, v114
	v_exp_f32_e32 v113, v113
	s_nop 0
	v_add_f32_e32 v113, 1.0, v113
	v_rcp_f32_e32 v113, v113
	s_nop 0
	v_max_f32_e32 v113, 0x219392ef, v113
	s_and_b64 vcc, exec, s[4:5]
	s_mov_b64 s[0:1], -1
	v_mul_f32_e32 v114, 0xbfb8aa3b, v115
	v_exp_f32_e32 v114, v114
	s_nop 0
	v_add_f32_e32 v114, 1.0, v114
	v_rcp_f32_e32 v114, v114
	s_nop 0
	v_max_f32_e32 v114, 0x219392ef, v114
	v_cvt_pk_bf16_f32 v116, v122, v116
	v_cvt_pk_bf16_f32 v117, v117, v118
	v_cvt_pk_bf16_f32 v118, v119, v112
	v_cvt_pk_bf16_f32 v119, v113, v114
	s_nop 0
	v_permlane16_swap_b32_e32 v116, v118
	v_permlane16_swap_b32_e32 v117, v119
	s_and_b64 vcc, exec, s[4:5]
	s_mov_b64 s[0:1], -1
	global_store_dwordx4 v[120:121], v[116:119], off offset:256
	v_mul_f32_e32 v112, 0xbfb8aa3b, v108
	v_exp_f32_e32 v112, v112
	s_nop 0
	v_add_f32_e32 v112, 1.0, v112
	v_rcp_f32_e32 v112, v112
	s_nop 0
	v_max_f32_e32 v112, 0x219392ef, v112
	s_and_b64 vcc, exec, s[4:5]
	s_mov_b64 s[0:1], -1
	v_mul_f32_e32 v108, 0xbfb8aa3b, v109
	v_exp_f32_e32 v108, v108
	s_nop 0
	v_add_f32_e32 v108, 1.0, v108
	v_rcp_f32_e32 v108, v108
	s_nop 0
	v_max_f32_e32 v108, 0x219392ef, v108
	s_and_b64 vcc, exec, s[4:5]
	s_mov_b64 s[0:1], -1
	v_mul_f32_e32 v109, 0xbfb8aa3b, v110
	v_exp_f32_e32 v109, v109
	s_nop 0
	v_add_f32_e32 v109, 1.0, v109
	v_rcp_f32_e32 v109, v109
	s_nop 0
	v_max_f32_e32 v109, 0x219392ef, v109
	s_and_b64 vcc, exec, s[4:5]
	s_mov_b64 s[0:1], -1
	v_mul_f32_e32 v110, 0xbfb8aa3b, v111
	v_exp_f32_e32 v110, v110
	s_nop 0
	v_add_f32_e32 v110, 1.0, v110
	v_rcp_f32_e32 v110, v110
	s_nop 0
	v_max_f32_e32 v110, 0x219392ef, v110
	s_and_b64 vcc, exec, s[4:5]
	s_mov_b64 s[0:1], -1
	v_mul_f32_e32 v111, 0xbfb8aa3b, v104
	v_exp_f32_e32 v111, v111
	s_nop 0
	v_add_f32_e32 v111, 1.0, v111
	v_rcp_f32_e32 v111, v111
	s_nop 0
	v_max_f32_e32 v111, 0x219392ef, v111
	s_and_b64 vcc, exec, s[4:5]
	s_mov_b64 s[0:1], -1
	v_mul_f32_e32 v104, 0xbfb8aa3b, v105
	v_exp_f32_e32 v104, v104
	s_nop 0
	v_add_f32_e32 v104, 1.0, v104
	v_rcp_f32_e32 v104, v104
	s_nop 0
	v_max_f32_e32 v104, 0x219392ef, v104
	s_and_b64 vcc, exec, s[4:5]
	s_mov_b64 s[0:1], -1
	v_mul_f32_e32 v105, 0xbfb8aa3b, v106
	v_exp_f32_e32 v105, v105
	s_nop 0
	v_add_f32_e32 v105, 1.0, v105
	v_rcp_f32_e32 v105, v105
	s_nop 0
	v_max_f32_e32 v105, 0x219392ef, v105
	s_and_b64 vcc, exec, s[4:5]
	s_mov_b64 s[0:1], -1
	v_mul_f32_e32 v106, 0xbfb8aa3b, v107
	v_exp_f32_e32 v106, v106
	s_nop 0
	v_add_f32_e32 v106, 1.0, v106
	v_rcp_f32_e32 v106, v106
	s_nop 0
	v_max_f32_e32 v106, 0x219392ef, v106
	v_cvt_pk_bf16_f32 v109, v109, v110
	v_cvt_pk_bf16_f32 v110, v111, v104
	v_add_co_u32_e32 v104, vcc, 0x10000, v120
	v_cvt_pk_bf16_f32 v108, v112, v108
	v_cvt_pk_bf16_f32 v111, v105, v106
	v_addc_co_u32_e32 v105, vcc, 0, v121, vcc
	v_permlane16_swap_b32_e32 v108, v110
	v_permlane16_swap_b32_e32 v109, v111
	s_and_b64 vcc, exec, s[4:5]
	s_mov_b64 s[0:1], -1
	global_store_dwordx4 v[104:105], v[108:111], off
	v_mul_f32_e32 v104, 0xbfb8aa3b, v100
	v_exp_f32_e32 v104, v104
	s_nop 0
	v_add_f32_e32 v104, 1.0, v104
	v_rcp_f32_e32 v104, v104
	s_nop 0
	v_max_f32_e32 v104, 0x219392ef, v104
	s_and_b64 vcc, exec, s[4:5]
	s_mov_b64 s[0:1], -1
	v_mul_f32_e32 v100, 0xbfb8aa3b, v101
	v_exp_f32_e32 v100, v100
	s_nop 0
	v_add_f32_e32 v100, 1.0, v100
	v_rcp_f32_e32 v100, v100
	s_nop 0
	v_max_f32_e32 v100, 0x219392ef, v100
	s_and_b64 vcc, exec, s[4:5]
	s_mov_b64 s[0:1], -1
	v_mul_f32_e32 v101, 0xbfb8aa3b, v102
	v_exp_f32_e32 v101, v101
; __device__ __forceinline__ float sigmoidf_(float v) { return __builtin_amdgcn_rcpf(1.f + __expf(-v)); }
;     ...
;   } else {
;     u16* out = (u16*)outv + (size_t)(brow + wr * 64 + fr) * pitch + col0 + wc * 32 + (fq & 1) * 16 + (fq >> 1) * 8;
; #pragma unroll
;     for (int m = 0; m < 8; ++m)
; #pragma unroll
;       for (int np = 0; np < 2; ++np) {
;         unsigned pk[2][2];
; #pragma unroll
;         for (int h = 0; h < 2; ++h) {
;           float v[4];
; #pragma unroll
;           for (int j = 0; j < 4; ++j) {
;             v[j] = acc[m][2 * np + h][j];
;             v[j] = mode ? fmaxf(sigmoidf_(v[j]), 1e-18f) : v[j] * scale;
;           }
;           pk[h][0] = pack2(v[0], v[1]);
;           pk[h][1] = pack2(v[2], v[3]);
;         }
;         *(i32x4*)(out + (size_t)ROWOFF(m) * pitch + COLOFF(2 * np)) = widen_pair(pk[0][0], pk[0][1], pk[1][0], pk[1][1]);
;       }
;   }
	s_nop 0
	v_add_f32_e32 v101, 1.0, v101
	v_rcp_f32_e32 v101, v101
	s_nop 0
	v_max_f32_e32 v101, 0x219392ef, v101
	s_and_b64 vcc, exec, s[4:5]
	s_mov_b64 s[0:1], -1
	v_mul_f32_e32 v102, 0xbfb8aa3b, v103
	v_exp_f32_e32 v102, v102
	s_nop 0
	v_add_f32_e32 v102, 1.0, v102
	v_rcp_f32_e32 v102, v102
	s_nop 0
	v_max_f32_e32 v102, 0x219392ef, v102
	s_and_b64 vcc, exec, s[4:5]
	s_mov_b64 s[0:1], -1
	v_mul_f32_e32 v103, 0xbfb8aa3b, v96
	v_exp_f32_e32 v103, v103
	s_nop 0
	v_add_f32_e32 v103, 1.0, v103
	v_rcp_f32_e32 v103, v103
	s_nop 0
	v_max_f32_e32 v103, 0x219392ef, v103
	s_and_b64 vcc, exec, s[4:5]
	s_mov_b64 s[0:1], -1
	v_mul_f32_e32 v96, 0xbfb8aa3b, v97
	v_exp_f32_e32 v96, v96
	s_nop 0
	v_add_f32_e32 v96, 1.0, v96
	v_rcp_f32_e32 v96, v96
	s_nop 0
	v_max_f32_e32 v96, 0x219392ef, v96
	s_and_b64 vcc, exec, s[4:5]
	s_mov_b64 s[0:1], -1
	v_mul_f32_e32 v97, 0xbfb8aa3b, v98
	v_exp_f32_e32 v97, v97
	s_nop 0
	v_add_f32_e32 v97, 1.0, v97
	v_rcp_f32_e32 v97, v97
	s_nop 0
	v_max_f32_e32 v97, 0x219392ef, v97
	s_and_b64 vcc, exec, s[4:5]
	s_mov_b64 s[0:1], -1
	v_mul_f32_e32 v98, 0xbfb8aa3b, v99
	v_exp_f32_e32 v98, v98
	s_nop 0
	v_add_f32_e32 v98, 1.0, v98
	v_rcp_f32_e32 v98, v98
	s_nop 0
	v_max_f32_e32 v98, 0x219392ef, v98
	v_cvt_pk_bf16_f32 v101, v101, v102
	v_cvt_pk_bf16_f32 v102, v103, v96
	v_add_co_u32_e32 v96, vcc, 0x10000, v120
	v_cvt_pk_bf16_f32 v100, v104, v100
	v_cvt_pk_bf16_f32 v103, v97, v98
	v_addc_co_u32_e32 v97, vcc, 0, v121, vcc
	v_permlane16_swap_b32_e32 v100, v102
	v_permlane16_swap_b32_e32 v101, v103
	s_and_b64 vcc, exec, s[4:5]
	s_mov_b64 s[0:1], -1
	global_store_dwordx4 v[96:97], v[100:103], off offset:256
	v_mul_f32_e32 v96, 0xbfb8aa3b, v92
	v_exp_f32_e32 v96, v96
	s_nop 0
	v_add_f32_e32 v96, 1.0, v96
	v_rcp_f32_e32 v96, v96
	s_nop 0
	v_max_f32_e32 v96, 0x219392ef, v96
	s_and_b64 vcc, exec, s[4:5]
	s_mov_b64 s[0:1], -1
	v_mul_f32_e32 v92, 0xbfb8aa3b, v93
	v_exp_f32_e32 v92, v92
	s_nop 0
	v_add_f32_e32 v92, 1.0, v92
	v_rcp_f32_e32 v92, v92
	s_nop 0
	v_max_f32_e32 v92, 0x219392ef, v92
	s_and_b64 vcc, exec, s[4:5]
	s_mov_b64 s[0:1], -1
	v_mul_f32_e32 v93, 0xbfb8aa3b, v94
	v_exp_f32_e32 v93, v93
	s_nop 0
	v_add_f32_e32 v93, 1.0, v93
	v_rcp_f32_e32 v93, v93
	s_nop 0
	v_max_f32_e32 v93, 0x219392ef, v93
	s_and_b64 vcc, exec, s[4:5]
	s_mov_b64 s[0:1], -1
	v_mul_f32_e32 v94, 0xbfb8aa3b, v95
	v_exp_f32_e32 v94, v94
	s_nop 0
	v_add_f32_e32 v94, 1.0, v94
	v_rcp_f32_e32 v94, v94
	s_nop 0
	v_max_f32_e32 v94, 0x219392ef, v94
	s_and_b64 vcc, exec, s[4:5]
	s_mov_b64 s[0:1], -1
	v_mul_f32_e32 v95, 0xbfb8aa3b, v88
	v_exp_f32_e32 v95, v95
	s_nop 0
	v_add_f32_e32 v95, 1.0, v95
	v_rcp_f32_e32 v95, v95
	s_nop 0
	v_max_f32_e32 v95, 0x219392ef, v95
	s_and_b64 vcc, exec, s[4:5]
	s_mov_b64 s[0:1], -1
	v_mul_f32_e32 v88, 0xbfb8aa3b, v89
	v_exp_f32_e32 v88, v88
	s_nop 0
	v_add_f32_e32 v88, 1.0, v88
	v_rcp_f32_e32 v88, v88
	s_nop 0
	v_max_f32_e32 v88, 0x219392ef, v88
	s_and_b64 vcc, exec, s[4:5]
	s_mov_b64 s[0:1], -1
	v_mul_f32_e32 v89, 0xbfb8aa3b, v90
	v_exp_f32_e32 v89, v89
	s_nop 0
	v_add_f32_e32 v89, 1.0, v89
	v_rcp_f32_e32 v89, v89
	s_nop 0
	v_max_f32_e32 v89, 0x219392ef, v89
	s_and_b64 vcc, exec, s[4:5]
	s_mov_b64 s[0:1], -1
	v_mul_f32_e32 v90, 0xbfb8aa3b, v91
	v_exp_f32_e32 v90, v90
	s_nop 0
	v_add_f32_e32 v90, 1.0, v90
	v_rcp_f32_e32 v90, v90
	s_nop 0
	v_max_f32_e32 v90, 0x219392ef, v90
	v_cvt_pk_bf16_f32 v93, v93, v94
	v_cvt_pk_bf16_f32 v94, v95, v88
	v_add_co_u32_e32 v88, vcc, 0x20000, v120
	v_cvt_pk_bf16_f32 v92, v96, v92
	v_cvt_pk_bf16_f32 v95, v89, v90
	v_addc_co_u32_e32 v89, vcc, 0, v121, vcc
	v_permlane16_swap_b32_e32 v92, v94
	v_permlane16_swap_b32_e32 v93, v95
	s_and_b64 vcc, exec, s[4:5]
	s_mov_b64 s[0:1], -1
	global_store_dwordx4 v[88:89], v[92:95], off
	v_mul_f32_e32 v88, 0xbfb8aa3b, v84
	v_exp_f32_e32 v88, v88
	s_nop 0
	v_add_f32_e32 v88, 1.0, v88
	v_rcp_f32_e32 v88, v88
	s_nop 0
	v_max_f32_e32 v88, 0x219392ef, v88
	s_and_b64 vcc, exec, s[4:5]
	s_mov_b64 s[0:1], -1
	v_mul_f32_e32 v84, 0xbfb8aa3b, v85
	v_exp_f32_e32 v84, v84
	s_nop 0
	v_add_f32_e32 v84, 1.0, v84
	v_rcp_f32_e32 v84, v84
	s_nop 0
	v_max_f32_e32 v84, 0x219392ef, v84
	s_and_b64 vcc, exec, s[4:5]
	s_mov_b64 s[0:1], -1
	v_mul_f32_e32 v85, 0xbfb8aa3b, v86
	v_exp_f32_e32 v85, v85
	s_nop 0
	v_add_f32_e32 v85, 1.0, v85
	v_rcp_f32_e32 v85, v85
	s_nop 0
	v_max_f32_e32 v85, 0x219392ef, v85
	s_and_b64 vcc, exec, s[4:5]
	s_mov_b64 s[0:1], -1
	v_mul_f32_e32 v86, 0xbfb8aa3b, v87
	v_exp_f32_e32 v86, v86
	s_nop 0
	v_add_f32_e32 v86, 1.0, v86
	v_rcp_f32_e32 v86, v86
	s_nop 0
	v_max_f32_e32 v86, 0x219392ef, v86
	s_and_b64 vcc, exec, s[4:5]
	s_mov_b64 s[0:1], -1
	v_mul_f32_e32 v87, 0xbfb8aa3b, v80
	v_exp_f32_e32 v87, v87
	s_nop 0
	v_add_f32_e32 v87, 1.0, v87
	v_rcp_f32_e32 v87, v87
	s_nop 0
	v_max_f32_e32 v87, 0x219392ef, v87
	s_and_b64 vcc, exec, s[4:5]
	s_mov_b64 s[0:1], -1
	v_mul_f32_e32 v80, 0xbfb8aa3b, v81
	v_exp_f32_e32 v80, v80
	s_nop 0
	v_add_f32_e32 v80, 1.0, v80
	v_rcp_f32_e32 v80, v80
	s_nop 0
	v_max_f32_e32 v80, 0x219392ef, v80
	s_and_b64 vcc, exec, s[4:5]
	s_mov_b64 s[0:1], -1
	v_mul_f32_e32 v81, 0xbfb8aa3b, v82
	v_exp_f32_e32 v81, v81
	s_nop 0
	v_add_f32_e32 v81, 1.0, v81
	v_rcp_f32_e32 v81, v81
	s_nop 0
	v_max_f32_e32 v81, 0x219392ef, v81
	s_and_b64 vcc, exec, s[4:5]
	s_mov_b64 s[0:1], -1
	v_mul_f32_e32 v82, 0xbfb8aa3b, v83
	v_exp_f32_e32 v82, v82
	s_nop 0
	v_add_f32_e32 v82, 1.0, v82
	v_rcp_f32_e32 v82, v82
	s_nop 0
	v_max_f32_e32 v82, 0x219392ef, v82
	v_cvt_pk_bf16_f32 v85, v85, v86
	v_cvt_pk_bf16_f32 v86, v87, v80
	v_add_co_u32_e32 v80, vcc, 0x20000, v120
	v_cvt_pk_bf16_f32 v84, v88, v84
	v_cvt_pk_bf16_f32 v87, v81, v82
	v_addc_co_u32_e32 v81, vcc, 0, v121, vcc
	v_permlane16_swap_b32_e32 v84, v86
; __device__ __forceinline__ float sigmoidf_(float v) { return __builtin_amdgcn_rcpf(1.f + __expf(-v)); }
;     ...
;   } else {
;     u16* out = (u16*)outv + (size_t)(brow + wr * 64 + fr) * pitch + col0 + wc * 32 + (fq & 1) * 16 + (fq >> 1) * 8;
; #pragma unroll
;     for (int m = 0; m < 8; ++m)
; #pragma unroll
;       for (int np = 0; np < 2; ++np) {
;         unsigned pk[2][2];
; #pragma unroll
;         for (int h = 0; h < 2; ++h) {
;           float v[4];
; #pragma unroll
;           for (int j = 0; j < 4; ++j) {
;             v[j] = acc[m][2 * np + h][j];
;             v[j] = mode ? fmaxf(sigmoidf_(v[j]), 1e-18f) : v[j] * scale;
;           }
;           pk[h][0] = pack2(v[0], v[1]);
;           pk[h][1] = pack2(v[2], v[3]);
;         }
;         *(i32x4*)(out + (size_t)ROWOFF(m) * pitch + COLOFF(2 * np)) = widen_pair(pk[0][0], pk[0][1], pk[1][0], pk[1][1]);
;       }
;   }
	v_permlane16_swap_b32_e32 v85, v87
	s_and_b64 vcc, exec, s[4:5]
	s_mov_b64 s[0:1], -1
	global_store_dwordx4 v[80:81], v[84:87], off offset:256
	v_mul_f32_e32 v80, 0xbfb8aa3b, v76
	v_exp_f32_e32 v80, v80
	s_nop 0
	v_add_f32_e32 v80, 1.0, v80
	v_rcp_f32_e32 v80, v80
	s_nop 0
	v_max_f32_e32 v80, 0x219392ef, v80
	s_and_b64 vcc, exec, s[4:5]
	s_mov_b64 s[0:1], -1
	v_mul_f32_e32 v76, 0xbfb8aa3b, v77
	v_exp_f32_e32 v76, v76
	s_nop 0
	v_add_f32_e32 v76, 1.0, v76
	v_rcp_f32_e32 v76, v76
	s_nop 0
	v_max_f32_e32 v76, 0x219392ef, v76
	s_and_b64 vcc, exec, s[4:5]
	s_mov_b64 s[0:1], -1
	v_mul_f32_e32 v77, 0xbfb8aa3b, v78
	v_exp_f32_e32 v77, v77
	s_nop 0
	v_add_f32_e32 v77, 1.0, v77
	v_rcp_f32_e32 v77, v77
	s_nop 0
	v_max_f32_e32 v77, 0x219392ef, v77
	s_and_b64 vcc, exec, s[4:5]
	s_mov_b64 s[0:1], -1
	v_mul_f32_e32 v78, 0xbfb8aa3b, v79
	v_exp_f32_e32 v78, v78
	s_nop 0
	v_add_f32_e32 v78, 1.0, v78
	v_rcp_f32_e32 v78, v78
	s_nop 0
	v_max_f32_e32 v78, 0x219392ef, v78
	s_and_b64 vcc, exec, s[4:5]
	s_mov_b64 s[0:1], -1
	v_mul_f32_e32 v79, 0xbfb8aa3b, v72
	v_exp_f32_e32 v79, v79
	s_nop 0
	v_add_f32_e32 v79, 1.0, v79
	v_rcp_f32_e32 v79, v79
	s_nop 0
	v_max_f32_e32 v79, 0x219392ef, v79
	s_and_b64 vcc, exec, s[4:5]
	s_mov_b64 s[0:1], -1
	v_mul_f32_e32 v72, 0xbfb8aa3b, v73
	v_exp_f32_e32 v72, v72
	s_nop 0
	v_add_f32_e32 v72, 1.0, v72
	v_rcp_f32_e32 v72, v72
	s_nop 0
	v_max_f32_e32 v72, 0x219392ef, v72
	s_and_b64 vcc, exec, s[4:5]
	s_mov_b64 s[0:1], -1
	v_mul_f32_e32 v73, 0xbfb8aa3b, v74
	v_exp_f32_e32 v73, v73
	s_nop 0
	v_add_f32_e32 v73, 1.0, v73
	v_rcp_f32_e32 v73, v73
	s_nop 0
	v_max_f32_e32 v73, 0x219392ef, v73
	s_and_b64 vcc, exec, s[4:5]
	s_mov_b64 s[0:1], -1
	v_mul_f32_e32 v74, 0xbfb8aa3b, v75
	v_exp_f32_e32 v74, v74
	s_nop 0
	v_add_f32_e32 v74, 1.0, v74
	v_rcp_f32_e32 v74, v74
	s_nop 0
	v_max_f32_e32 v74, 0x219392ef, v74
	v_cvt_pk_bf16_f32 v77, v77, v78
	v_cvt_pk_bf16_f32 v78, v79, v72
	v_add_co_u32_e32 v72, vcc, 0x30000, v120
	v_cvt_pk_bf16_f32 v76, v80, v76
	v_cvt_pk_bf16_f32 v79, v73, v74
	v_addc_co_u32_e32 v73, vcc, 0, v121, vcc
	v_permlane16_swap_b32_e32 v76, v78
	v_permlane16_swap_b32_e32 v77, v79
	s_and_b64 vcc, exec, s[4:5]
	s_mov_b64 s[0:1], -1
	global_store_dwordx4 v[72:73], v[76:79], off
	v_mul_f32_e32 v72, 0xbfb8aa3b, v68
	v_exp_f32_e32 v72, v72
	s_nop 0
	v_add_f32_e32 v72, 1.0, v72
	v_rcp_f32_e32 v72, v72
	s_nop 0
	v_max_f32_e32 v72, 0x219392ef, v72
	s_and_b64 vcc, exec, s[4:5]
	s_mov_b64 s[0:1], -1
	v_mul_f32_e32 v68, 0xbfb8aa3b, v69
	v_exp_f32_e32 v68, v68
	s_nop 0
	v_add_f32_e32 v68, 1.0, v68
	v_rcp_f32_e32 v68, v68
	s_nop 0
	v_max_f32_e32 v68, 0x219392ef, v68
	s_and_b64 vcc, exec, s[4:5]
	s_mov_b64 s[0:1], -1
	v_mul_f32_e32 v69, 0xbfb8aa3b, v70
	v_exp_f32_e32 v69, v69
	s_nop 0
	v_add_f32_e32 v69, 1.0, v69
	v_rcp_f32_e32 v69, v69
	s_nop 0
	v_max_f32_e32 v69, 0x219392ef, v69
	s_and_b64 vcc, exec, s[4:5]
	s_mov_b64 s[0:1], -1
	v_mul_f32_e32 v70, 0xbfb8aa3b, v71
	v_exp_f32_e32 v70, v70
	s_nop 0
	v_add_f32_e32 v70, 1.0, v70
	v_rcp_f32_e32 v70, v70
	s_nop 0
	v_max_f32_e32 v70, 0x219392ef, v70
	s_and_b64 vcc, exec, s[4:5]
	s_mov_b64 s[0:1], -1
	v_mul_f32_e32 v71, 0xbfb8aa3b, v64
	v_exp_f32_e32 v71, v71
	s_nop 0
	v_add_f32_e32 v71, 1.0, v71
	v_rcp_f32_e32 v71, v71
	s_nop 0
	v_max_f32_e32 v71, 0x219392ef, v71
	s_and_b64 vcc, exec, s[4:5]
	s_mov_b64 s[0:1], -1
	v_mul_f32_e32 v64, 0xbfb8aa3b, v65
	v_exp_f32_e32 v64, v64
	s_nop 0
	v_add_f32_e32 v64, 1.0, v64
	v_rcp_f32_e32 v64, v64
	s_nop 0
	v_max_f32_e32 v64, 0x219392ef, v64
	s_and_b64 vcc, exec, s[4:5]
	s_mov_b64 s[0:1], -1
	v_mul_f32_e32 v65, 0xbfb8aa3b, v66
	v_exp_f32_e32 v65, v65
	s_nop 0
	v_add_f32_e32 v65, 1.0, v65
	v_rcp_f32_e32 v65, v65
	s_nop 0
	v_max_f32_e32 v65, 0x219392ef, v65
	s_and_b64 vcc, exec, s[4:5]
	s_mov_b64 s[0:1], -1
	v_mul_f32_e32 v66, 0xbfb8aa3b, v67
	v_exp_f32_e32 v66, v66
	s_nop 0
	v_add_f32_e32 v66, 1.0, v66
	v_rcp_f32_e32 v66, v66
	s_nop 0
	v_max_f32_e32 v66, 0x219392ef, v66
	v_cvt_pk_bf16_f32 v69, v69, v70
	v_cvt_pk_bf16_f32 v70, v71, v64
	v_add_co_u32_e32 v64, vcc, 0x30000, v120
	v_cvt_pk_bf16_f32 v68, v72, v68
	v_cvt_pk_bf16_f32 v71, v65, v66
	v_addc_co_u32_e32 v65, vcc, 0, v121, vcc
	v_permlane16_swap_b32_e32 v68, v70
	v_permlane16_swap_b32_e32 v69, v71
	s_and_b64 vcc, exec, s[4:5]
	s_mov_b64 s[0:1], -1
	global_store_dwordx4 v[64:65], v[68:71], off offset:256
	v_mul_f32_e32 v64, 0xbfb8aa3b, v60
	v_exp_f32_e32 v64, v64
	s_nop 0
	v_add_f32_e32 v64, 1.0, v64
	v_rcp_f32_e32 v64, v64
	s_nop 0
	v_max_f32_e32 v64, 0x219392ef, v64
	s_and_b64 vcc, exec, s[4:5]
	s_mov_b64 s[0:1], -1
	v_mul_f32_e32 v60, 0xbfb8aa3b, v61
	v_exp_f32_e32 v60, v60
	s_nop 0
	v_add_f32_e32 v60, 1.0, v60
	v_rcp_f32_e32 v60, v60
	s_nop 0
	v_max_f32_e32 v60, 0x219392ef, v60
	s_and_b64 vcc, exec, s[4:5]
	s_mov_b64 s[0:1], -1
	v_mul_f32_e32 v61, 0xbfb8aa3b, v62
	v_exp_f32_e32 v61, v61
	s_nop 0
	v_add_f32_e32 v61, 1.0, v61
	v_rcp_f32_e32 v61, v61
	s_nop 0
	v_max_f32_e32 v61, 0x219392ef, v61
	s_and_b64 vcc, exec, s[4:5]
	s_mov_b64 s[0:1], -1
	v_mul_f32_e32 v62, 0xbfb8aa3b, v63
	v_exp_f32_e32 v62, v62
	s_nop 0
	v_add_f32_e32 v62, 1.0, v62
	v_rcp_f32_e32 v62, v62
	s_nop 0
	v_max_f32_e32 v62, 0x219392ef, v62
	s_and_b64 vcc, exec, s[4:5]
	s_mov_b64 s[0:1], -1
	v_mul_f32_e32 v63, 0xbfb8aa3b, v56
	v_exp_f32_e32 v63, v63
	s_nop 0
	v_add_f32_e32 v63, 1.0, v63
	v_rcp_f32_e32 v63, v63
	s_nop 0
	v_max_f32_e32 v63, 0x219392ef, v63
	s_and_b64 vcc, exec, s[4:5]
	s_mov_b64 s[0:1], -1
	v_mul_f32_e32 v56, 0xbfb8aa3b, v57
	v_exp_f32_e32 v56, v56
	s_nop 0
	v_add_f32_e32 v56, 1.0, v56
	v_rcp_f32_e32 v56, v56
	s_nop 0
	v_max_f32_e32 v56, 0x219392ef, v56
	s_and_b64 vcc, exec, s[4:5]
	s_mov_b64 s[0:1], -1
	v_mul_f32_e32 v57, 0xbfb8aa3b, v58
; __device__ __forceinline__ float sigmoidf_(float v) { return __builtin_amdgcn_rcpf(1.f + __expf(-v)); }
;     ...
;   } else {
;     u16* out = (u16*)outv + (size_t)(brow + wr * 64 + fr) * pitch + col0 + wc * 32 + (fq & 1) * 16 + (fq >> 1) * 8;
; #pragma unroll
;     for (int m = 0; m < 8; ++m)
; #pragma unroll
;       for (int np = 0; np < 2; ++np) {
;         unsigned pk[2][2];
; #pragma unroll
;         for (int h = 0; h < 2; ++h) {
;           float v[4];
; #pragma unroll
;           for (int j = 0; j < 4; ++j) {
;             v[j] = acc[m][2 * np + h][j];
;             v[j] = mode ? fmaxf(sigmoidf_(v[j]), 1e-18f) : v[j] * scale;
;           }
;           pk[h][0] = pack2(v[0], v[1]);
;           pk[h][1] = pack2(v[2], v[3]);
;         }
;         *(i32x4*)(out + (size_t)ROWOFF(m) * pitch + COLOFF(2 * np)) = widen_pair(pk[0][0], pk[0][1], pk[1][0], pk[1][1]);
;       }
;   }
	v_exp_f32_e32 v57, v57
	s_nop 0
	v_add_f32_e32 v57, 1.0, v57
	v_rcp_f32_e32 v57, v57
	s_nop 0
	v_max_f32_e32 v57, 0x219392ef, v57
	s_and_b64 vcc, exec, s[4:5]
	s_mov_b64 s[0:1], -1
	v_mul_f32_e32 v58, 0xbfb8aa3b, v59
	v_exp_f32_e32 v58, v58
	s_nop 0
	v_add_f32_e32 v58, 1.0, v58
	v_rcp_f32_e32 v58, v58
	s_nop 0
	v_max_f32_e32 v58, 0x219392ef, v58
	v_cvt_pk_bf16_f32 v61, v61, v62
	v_cvt_pk_bf16_f32 v62, v63, v56
	v_add_co_u32_e32 v56, vcc, 0x80000, v120
	v_cvt_pk_bf16_f32 v60, v64, v60
	v_cvt_pk_bf16_f32 v63, v57, v58
	v_addc_co_u32_e32 v57, vcc, 0, v121, vcc
	v_permlane16_swap_b32_e32 v60, v62
	v_permlane16_swap_b32_e32 v61, v63
	s_and_b64 vcc, exec, s[4:5]
	s_mov_b64 s[0:1], -1
	global_store_dwordx4 v[56:57], v[60:63], off
	v_mul_f32_e32 v56, 0xbfb8aa3b, v52
	v_exp_f32_e32 v56, v56
	s_nop 0
	v_add_f32_e32 v56, 1.0, v56
	v_rcp_f32_e32 v56, v56
	s_nop 0
	v_max_f32_e32 v56, 0x219392ef, v56
	s_and_b64 vcc, exec, s[4:5]
	s_mov_b64 s[0:1], -1
	v_mul_f32_e32 v52, 0xbfb8aa3b, v53
	v_exp_f32_e32 v52, v52
	s_nop 0
	v_add_f32_e32 v52, 1.0, v52
	v_rcp_f32_e32 v52, v52
	s_nop 0
	v_max_f32_e32 v52, 0x219392ef, v52
	s_and_b64 vcc, exec, s[4:5]
	s_mov_b64 s[0:1], -1
	v_mul_f32_e32 v53, 0xbfb8aa3b, v54
	v_exp_f32_e32 v53, v53
	s_nop 0
	v_add_f32_e32 v53, 1.0, v53
	v_rcp_f32_e32 v53, v53
	s_nop 0
	v_max_f32_e32 v53, 0x219392ef, v53
	s_and_b64 vcc, exec, s[4:5]
	s_mov_b64 s[0:1], -1
	v_mul_f32_e32 v54, 0xbfb8aa3b, v55
	v_exp_f32_e32 v54, v54
	s_nop 0
	v_add_f32_e32 v54, 1.0, v54
	v_rcp_f32_e32 v54, v54
	s_nop 0
	v_max_f32_e32 v54, 0x219392ef, v54
	s_and_b64 vcc, exec, s[4:5]
	s_mov_b64 s[0:1], -1
	v_mul_f32_e32 v55, 0xbfb8aa3b, v48
	v_exp_f32_e32 v55, v55
	s_nop 0
	v_add_f32_e32 v55, 1.0, v55
	v_rcp_f32_e32 v55, v55
	s_nop 0
	v_max_f32_e32 v55, 0x219392ef, v55
	s_and_b64 vcc, exec, s[4:5]
	s_mov_b64 s[0:1], -1
	v_mul_f32_e32 v48, 0xbfb8aa3b, v49
	v_exp_f32_e32 v48, v48
	s_nop 0
	v_add_f32_e32 v48, 1.0, v48
	v_rcp_f32_e32 v48, v48
	s_nop 0
	v_max_f32_e32 v48, 0x219392ef, v48
	s_and_b64 vcc, exec, s[4:5]
	s_mov_b64 s[0:1], -1
	v_mul_f32_e32 v49, 0xbfb8aa3b, v50
	v_exp_f32_e32 v49, v49
	s_nop 0
	v_add_f32_e32 v49, 1.0, v49
	v_rcp_f32_e32 v49, v49
	s_nop 0
	v_max_f32_e32 v49, 0x219392ef, v49
	s_and_b64 vcc, exec, s[4:5]
	s_mov_b64 s[0:1], -1
	v_mul_f32_e32 v50, 0xbfb8aa3b, v51
	v_exp_f32_e32 v50, v50
	s_nop 0
	v_add_f32_e32 v50, 1.0, v50
	v_rcp_f32_e32 v50, v50
	s_nop 0
	v_max_f32_e32 v50, 0x219392ef, v50
	v_cvt_pk_bf16_f32 v53, v53, v54
	v_cvt_pk_bf16_f32 v54, v55, v48
	v_add_co_u32_e32 v48, vcc, 0x80000, v120
	v_cvt_pk_bf16_f32 v52, v56, v52
	v_cvt_pk_bf16_f32 v55, v49, v50
	v_addc_co_u32_e32 v49, vcc, 0, v121, vcc
	v_permlane16_swap_b32_e32 v52, v54
	v_permlane16_swap_b32_e32 v53, v55
	s_and_b64 vcc, exec, s[4:5]
	s_mov_b64 s[0:1], -1
	global_store_dwordx4 v[48:49], v[52:55], off offset:256
	v_mul_f32_e32 v48, 0xbfb8aa3b, v44
	v_exp_f32_e32 v48, v48
	s_nop 0
	v_add_f32_e32 v48, 1.0, v48
	v_rcp_f32_e32 v48, v48
	s_nop 0
	v_max_f32_e32 v48, 0x219392ef, v48
	s_and_b64 vcc, exec, s[4:5]
	s_mov_b64 s[0:1], -1
	v_mul_f32_e32 v44, 0xbfb8aa3b, v45
	v_exp_f32_e32 v44, v44
	s_nop 0
	v_add_f32_e32 v44, 1.0, v44
	v_rcp_f32_e32 v44, v44
	s_nop 0
	v_max_f32_e32 v44, 0x219392ef, v44
	s_and_b64 vcc, exec, s[4:5]
	s_mov_b64 s[0:1], -1
	v_mul_f32_e32 v45, 0xbfb8aa3b, v46
	v_exp_f32_e32 v45, v45
	s_nop 0
	v_add_f32_e32 v45, 1.0, v45
	v_rcp_f32_e32 v45, v45
	s_nop 0
	v_max_f32_e32 v45, 0x219392ef, v45
	s_and_b64 vcc, exec, s[4:5]
	s_mov_b64 s[0:1], -1
	v_mul_f32_e32 v46, 0xbfb8aa3b, v47
	v_exp_f32_e32 v46, v46
	s_nop 0
	v_add_f32_e32 v46, 1.0, v46
	v_rcp_f32_e32 v46, v46
	s_nop 0
	v_max_f32_e32 v46, 0x219392ef, v46
	s_and_b64 vcc, exec, s[4:5]
	s_mov_b64 s[0:1], -1
	v_mul_f32_e32 v47, 0xbfb8aa3b, v40
	v_exp_f32_e32 v47, v47
	s_nop 0
	v_add_f32_e32 v47, 1.0, v47
	v_rcp_f32_e32 v47, v47
	s_nop 0
	v_max_f32_e32 v47, 0x219392ef, v47
	s_and_b64 vcc, exec, s[4:5]
	s_mov_b64 s[0:1], -1
	v_mul_f32_e32 v40, 0xbfb8aa3b, v41
	v_exp_f32_e32 v40, v40
	s_nop 0
	v_add_f32_e32 v40, 1.0, v40
	v_rcp_f32_e32 v40, v40
	s_nop 0
	v_max_f32_e32 v40, 0x219392ef, v40
	s_and_b64 vcc, exec, s[4:5]
	s_mov_b64 s[0:1], -1
	v_mul_f32_e32 v41, 0xbfb8aa3b, v42
	v_exp_f32_e32 v41, v41
	s_nop 0
	v_add_f32_e32 v41, 1.0, v41
	v_rcp_f32_e32 v41, v41
	s_nop 0
	v_max_f32_e32 v41, 0x219392ef, v41
	s_and_b64 vcc, exec, s[4:5]
	s_mov_b64 s[0:1], -1
	v_mul_f32_e32 v42, 0xbfb8aa3b, v43
	v_exp_f32_e32 v42, v42
	s_nop 0
	v_add_f32_e32 v42, 1.0, v42
	v_rcp_f32_e32 v42, v42
	s_nop 0
	v_max_f32_e32 v42, 0x219392ef, v42
	v_cvt_pk_bf16_f32 v45, v45, v46
	v_cvt_pk_bf16_f32 v46, v47, v40
	v_add_co_u32_e32 v40, vcc, 0x90000, v120
	v_cvt_pk_bf16_f32 v44, v48, v44
	v_cvt_pk_bf16_f32 v47, v41, v42
	v_addc_co_u32_e32 v41, vcc, 0, v121, vcc
	v_permlane16_swap_b32_e32 v44, v46
	v_permlane16_swap_b32_e32 v45, v47
	s_and_b64 vcc, exec, s[4:5]
	s_mov_b64 s[0:1], -1
	global_store_dwordx4 v[40:41], v[44:47], off
	v_mul_f32_e32 v40, 0xbfb8aa3b, v36
	v_exp_f32_e32 v40, v40
	s_nop 0
	v_add_f32_e32 v40, 1.0, v40
	v_rcp_f32_e32 v40, v40
	s_nop 0
	v_max_f32_e32 v40, 0x219392ef, v40
	s_and_b64 vcc, exec, s[4:5]
	s_mov_b64 s[0:1], -1
	v_mul_f32_e32 v36, 0xbfb8aa3b, v37
	v_exp_f32_e32 v36, v36
	s_nop 0
	v_add_f32_e32 v36, 1.0, v36
	v_rcp_f32_e32 v36, v36
	s_nop 0
	v_max_f32_e32 v36, 0x219392ef, v36
	s_and_b64 vcc, exec, s[4:5]
	s_mov_b64 s[0:1], -1
	v_mul_f32_e32 v37, 0xbfb8aa3b, v38
	v_exp_f32_e32 v37, v37
	s_nop 0
	v_add_f32_e32 v37, 1.0, v37
	v_rcp_f32_e32 v37, v37
	s_nop 0
	v_max_f32_e32 v37, 0x219392ef, v37
	s_and_b64 vcc, exec, s[4:5]
	s_mov_b64 s[0:1], -1
	v_mul_f32_e32 v38, 0xbfb8aa3b, v39
	v_exp_f32_e32 v38, v38
	s_nop 0
	v_add_f32_e32 v38, 1.0, v38
; __device__ __forceinline__ float sigmoidf_(float v) { return __builtin_amdgcn_rcpf(1.f + __expf(-v)); }
;     ...
;   } else {
;     u16* out = (u16*)outv + (size_t)(brow + wr * 64 + fr) * pitch + col0 + wc * 32 + (fq & 1) * 16 + (fq >> 1) * 8;
; #pragma unroll
;     for (int m = 0; m < 8; ++m)
; #pragma unroll
;       for (int np = 0; np < 2; ++np) {
;         unsigned pk[2][2];
; #pragma unroll
;         for (int h = 0; h < 2; ++h) {
;           float v[4];
; #pragma unroll
;           for (int j = 0; j < 4; ++j) {
;             v[j] = acc[m][2 * np + h][j];
;             v[j] = mode ? fmaxf(sigmoidf_(v[j]), 1e-18f) : v[j] * scale;
;           }
;           pk[h][0] = pack2(v[0], v[1]);
;           pk[h][1] = pack2(v[2], v[3]);
;         }
;         *(i32x4*)(out + (size_t)ROWOFF(m) * pitch + COLOFF(2 * np)) = widen_pair(pk[0][0], pk[0][1], pk[1][0], pk[1][1]);
;       }
;   }
	v_rcp_f32_e32 v38, v38
	s_nop 0
	v_max_f32_e32 v38, 0x219392ef, v38
	s_and_b64 vcc, exec, s[4:5]
	s_mov_b64 s[0:1], -1
	v_mul_f32_e32 v39, 0xbfb8aa3b, v32
	v_exp_f32_e32 v39, v39
	s_nop 0
	v_add_f32_e32 v39, 1.0, v39
	v_rcp_f32_e32 v39, v39
	s_nop 0
	v_max_f32_e32 v39, 0x219392ef, v39
	s_and_b64 vcc, exec, s[4:5]
	s_mov_b64 s[0:1], -1
	v_mul_f32_e32 v32, 0xbfb8aa3b, v33
	v_exp_f32_e32 v32, v32
	s_nop 0
	v_add_f32_e32 v32, 1.0, v32
	v_rcp_f32_e32 v32, v32
	s_nop 0
	v_max_f32_e32 v32, 0x219392ef, v32
	s_and_b64 vcc, exec, s[4:5]
	s_mov_b64 s[0:1], -1
	v_mul_f32_e32 v33, 0xbfb8aa3b, v34
	v_exp_f32_e32 v33, v33
	s_nop 0
	v_add_f32_e32 v33, 1.0, v33
	v_rcp_f32_e32 v33, v33
	s_nop 0
	v_max_f32_e32 v33, 0x219392ef, v33
	s_and_b64 vcc, exec, s[4:5]
	s_mov_b64 s[0:1], -1
	v_mul_f32_e32 v34, 0xbfb8aa3b, v35
	v_exp_f32_e32 v34, v34
	s_nop 0
	v_add_f32_e32 v34, 1.0, v34
	v_rcp_f32_e32 v34, v34
	s_nop 0
	v_max_f32_e32 v34, 0x219392ef, v34
	v_cvt_pk_bf16_f32 v37, v37, v38
	v_cvt_pk_bf16_f32 v38, v39, v32
	v_add_co_u32_e32 v32, vcc, 0x90000, v120
	v_cvt_pk_bf16_f32 v36, v40, v36
	v_cvt_pk_bf16_f32 v39, v33, v34
	v_addc_co_u32_e32 v33, vcc, 0, v121, vcc
	v_permlane16_swap_b32_e32 v36, v38
	v_permlane16_swap_b32_e32 v37, v39
	s_and_b64 vcc, exec, s[4:5]
	s_mov_b64 s[0:1], -1
	global_store_dwordx4 v[32:33], v[36:39], off offset:256
	v_mul_f32_e32 v32, 0xbfb8aa3b, v28
	v_exp_f32_e32 v32, v32
	s_nop 0
	v_add_f32_e32 v32, 1.0, v32
	v_rcp_f32_e32 v32, v32
	s_nop 0
	v_max_f32_e32 v32, 0x219392ef, v32
	s_and_b64 vcc, exec, s[4:5]
	s_mov_b64 s[0:1], -1
	v_mul_f32_e32 v28, 0xbfb8aa3b, v29
	v_exp_f32_e32 v28, v28
	s_nop 0
	v_add_f32_e32 v28, 1.0, v28
	v_rcp_f32_e32 v28, v28
	s_nop 0
	v_max_f32_e32 v28, 0x219392ef, v28
	s_and_b64 vcc, exec, s[4:5]
	s_mov_b64 s[0:1], -1
	v_mul_f32_e32 v29, 0xbfb8aa3b, v30
	v_exp_f32_e32 v29, v29
	s_nop 0
	v_add_f32_e32 v29, 1.0, v29
	v_rcp_f32_e32 v29, v29
	s_nop 0
	v_max_f32_e32 v29, 0x219392ef, v29
	s_and_b64 vcc, exec, s[4:5]
	s_mov_b64 s[0:1], -1
	v_mul_f32_e32 v30, 0xbfb8aa3b, v31
	v_exp_f32_e32 v30, v30
	s_nop 0
	v_add_f32_e32 v30, 1.0, v30
	v_rcp_f32_e32 v30, v30
	s_nop 0
	v_max_f32_e32 v30, 0x219392ef, v30
	s_and_b64 vcc, exec, s[4:5]
	s_mov_b64 s[0:1], -1
	v_mul_f32_e32 v31, 0xbfb8aa3b, v24
	v_exp_f32_e32 v31, v31
	s_nop 0
	v_add_f32_e32 v31, 1.0, v31
	v_rcp_f32_e32 v31, v31
	s_nop 0
	v_max_f32_e32 v31, 0x219392ef, v31
	s_and_b64 vcc, exec, s[4:5]
	s_mov_b64 s[0:1], -1
	v_mul_f32_e32 v24, 0xbfb8aa3b, v25
	v_exp_f32_e32 v24, v24
	s_nop 0
	v_add_f32_e32 v24, 1.0, v24
	v_rcp_f32_e32 v24, v24
	s_nop 0
	v_max_f32_e32 v24, 0x219392ef, v24
	s_and_b64 vcc, exec, s[4:5]
	s_mov_b64 s[0:1], -1
	v_mul_f32_e32 v25, 0xbfb8aa3b, v26
	v_exp_f32_e32 v25, v25
	s_nop 0
	v_add_f32_e32 v25, 1.0, v25
	v_rcp_f32_e32 v25, v25
	s_nop 0
	v_max_f32_e32 v25, 0x219392ef, v25
	s_and_b64 vcc, exec, s[4:5]
	s_mov_b64 s[0:1], -1
	v_mul_f32_e32 v26, 0xbfb8aa3b, v27
	v_exp_f32_e32 v26, v26
	s_nop 0
	v_add_f32_e32 v26, 1.0, v26
	v_rcp_f32_e32 v26, v26
	s_nop 0
	v_max_f32_e32 v26, 0x219392ef, v26
	v_cvt_pk_bf16_f32 v29, v29, v30
	v_cvt_pk_bf16_f32 v30, v31, v24
	v_add_co_u32_e32 v24, vcc, 0xa0000, v120
	v_cvt_pk_bf16_f32 v28, v32, v28
	v_cvt_pk_bf16_f32 v31, v25, v26
	v_addc_co_u32_e32 v25, vcc, 0, v121, vcc
	v_permlane16_swap_b32_e32 v28, v30
	v_permlane16_swap_b32_e32 v29, v31
	s_and_b64 vcc, exec, s[4:5]
	s_mov_b64 s[0:1], -1
	global_store_dwordx4 v[24:25], v[28:31], off
	v_mul_f32_e32 v24, 0xbfb8aa3b, v20
	v_exp_f32_e32 v24, v24
	s_nop 0
	v_add_f32_e32 v24, 1.0, v24
	v_rcp_f32_e32 v24, v24
	s_nop 0
	v_max_f32_e32 v24, 0x219392ef, v24
	s_and_b64 vcc, exec, s[4:5]
	s_mov_b64 s[0:1], -1
	v_mul_f32_e32 v20, 0xbfb8aa3b, v21
	v_exp_f32_e32 v20, v20
	s_nop 0
	v_add_f32_e32 v20, 1.0, v20
	v_rcp_f32_e32 v20, v20
	s_nop 0
	v_max_f32_e32 v20, 0x219392ef, v20
	s_and_b64 vcc, exec, s[4:5]
	s_mov_b64 s[0:1], -1
	v_mul_f32_e32 v21, 0xbfb8aa3b, v22
	v_exp_f32_e32 v21, v21
	s_nop 0
	v_add_f32_e32 v21, 1.0, v21
	v_rcp_f32_e32 v21, v21
	s_nop 0
	v_max_f32_e32 v21, 0x219392ef, v21
	s_and_b64 vcc, exec, s[4:5]
	s_mov_b64 s[0:1], -1
	v_mul_f32_e32 v22, 0xbfb8aa3b, v23
	v_exp_f32_e32 v22, v22
	s_nop 0
	v_add_f32_e32 v22, 1.0, v22
	v_rcp_f32_e32 v22, v22
	s_nop 0
	v_max_f32_e32 v22, 0x219392ef, v22
	s_and_b64 vcc, exec, s[4:5]
	s_mov_b64 s[0:1], -1
	v_mul_f32_e32 v23, 0xbfb8aa3b, v16
	v_exp_f32_e32 v23, v23
	s_nop 0
	v_add_f32_e32 v23, 1.0, v23
	v_rcp_f32_e32 v23, v23
	s_nop 0
	v_max_f32_e32 v23, 0x219392ef, v23
	s_and_b64 vcc, exec, s[4:5]
	s_mov_b64 s[0:1], -1
	v_mul_f32_e32 v16, 0xbfb8aa3b, v17
	v_exp_f32_e32 v16, v16
	s_nop 0
	v_add_f32_e32 v16, 1.0, v16
; __device__ __forceinline__ float sigmoidf_(float v) { return __builtin_amdgcn_rcpf(1.f + __expf(-v)); }
;     ...
;   } else {
;     u16* out = (u16*)outv + (size_t)(brow + wr * 64 + fr) * pitch + col0 + wc * 32 + (fq & 1) * 16 + (fq >> 1) * 8;
; #pragma unroll
;     for (int m = 0; m < 8; ++m)
; #pragma unroll
;       for (int np = 0; np < 2; ++np) {
;         unsigned pk[2][2];
; #pragma unroll
;         for (int h = 0; h < 2; ++h) {
;           float v[4];
; #pragma unroll
;           for (int j = 0; j < 4; ++j) {
;             v[j] = acc[m][2 * np + h][j];
;             v[j] = mode ? fmaxf(sigmoidf_(v[j]), 1e-18f) : v[j] * scale;
;           }
;           pk[h][0] = pack2(v[0], v[1]);
;           pk[h][1] = pack2(v[2], v[3]);
;         }
;         *(i32x4*)(out + (size_t)ROWOFF(m) * pitch + COLOFF(2 * np)) = widen_pair(pk[0][0], pk[0][1], pk[1][0], pk[1][1]);
;       }
;   }
	v_rcp_f32_e32 v16, v16
	s_nop 0
	v_max_f32_e32 v16, 0x219392ef, v16
	s_and_b64 vcc, exec, s[4:5]
	s_mov_b64 s[0:1], -1
	v_mul_f32_e32 v17, 0xbfb8aa3b, v18
	v_exp_f32_e32 v17, v17
	s_nop 0
	v_add_f32_e32 v17, 1.0, v17
	v_rcp_f32_e32 v17, v17
	s_nop 0
	v_max_f32_e32 v17, 0x219392ef, v17
	s_and_b64 vcc, exec, s[4:5]
	s_mov_b64 s[0:1], -1
	v_mul_f32_e32 v18, 0xbfb8aa3b, v19
	v_exp_f32_e32 v18, v18
	s_nop 0
	v_add_f32_e32 v18, 1.0, v18
	v_rcp_f32_e32 v18, v18
	s_nop 0
	v_max_f32_e32 v18, 0x219392ef, v18
	v_cvt_pk_bf16_f32 v21, v21, v22
	v_cvt_pk_bf16_f32 v22, v23, v16
	v_add_co_u32_e32 v16, vcc, 0xa0000, v120
	v_cvt_pk_bf16_f32 v20, v24, v20
	v_cvt_pk_bf16_f32 v23, v17, v18
	v_addc_co_u32_e32 v17, vcc, 0, v121, vcc
	v_permlane16_swap_b32_e32 v20, v22
	v_permlane16_swap_b32_e32 v21, v23
	s_and_b64 vcc, exec, s[4:5]
	s_mov_b64 s[0:1], -1
	global_store_dwordx4 v[16:17], v[20:23], off offset:256
	v_mul_f32_e32 v16, 0xbfb8aa3b, v12
	v_exp_f32_e32 v16, v16
	s_nop 0
	v_add_f32_e32 v16, 1.0, v16
	v_rcp_f32_e32 v16, v16
	s_nop 0
	v_max_f32_e32 v16, 0x219392ef, v16
	s_and_b64 vcc, exec, s[4:5]
	s_mov_b64 s[0:1], -1
	v_mul_f32_e32 v12, 0xbfb8aa3b, v13
	v_exp_f32_e32 v12, v12
	s_nop 0
	v_add_f32_e32 v12, 1.0, v12
	v_rcp_f32_e32 v12, v12
	s_nop 0
	v_max_f32_e32 v12, 0x219392ef, v12
	s_and_b64 vcc, exec, s[4:5]
	s_mov_b64 s[0:1], -1
	v_mul_f32_e32 v13, 0xbfb8aa3b, v14
	v_exp_f32_e32 v13, v13
	s_nop 0
	v_add_f32_e32 v13, 1.0, v13
	v_rcp_f32_e32 v13, v13
	s_nop 0
	v_max_f32_e32 v13, 0x219392ef, v13
	s_and_b64 vcc, exec, s[4:5]
	s_mov_b64 s[0:1], -1
	v_mul_f32_e32 v14, 0xbfb8aa3b, v15
	v_exp_f32_e32 v14, v14
	s_nop 0
	v_add_f32_e32 v14, 1.0, v14
	v_rcp_f32_e32 v14, v14
	s_nop 0
	v_max_f32_e32 v14, 0x219392ef, v14
	s_and_b64 vcc, exec, s[4:5]
	s_mov_b64 s[0:1], -1
	v_mul_f32_e32 v15, 0xbfb8aa3b, v8
	v_exp_f32_e32 v15, v15
	s_nop 0
	v_add_f32_e32 v15, 1.0, v15
	v_rcp_f32_e32 v15, v15
	s_nop 0
	v_max_f32_e32 v15, 0x219392ef, v15
	s_and_b64 vcc, exec, s[4:5]
	s_mov_b64 s[0:1], -1
	v_mul_f32_e32 v8, 0xbfb8aa3b, v9
	v_exp_f32_e32 v8, v8
	s_nop 0
	v_add_f32_e32 v8, 1.0, v8
	v_rcp_f32_e32 v8, v8
	s_nop 0
	v_max_f32_e32 v8, 0x219392ef, v8
	s_and_b64 vcc, exec, s[4:5]
	s_mov_b64 s[0:1], -1
	v_mul_f32_e32 v9, 0xbfb8aa3b, v10
	v_exp_f32_e32 v9, v9
	s_nop 0
	v_add_f32_e32 v9, 1.0, v9
	v_rcp_f32_e32 v9, v9
	s_nop 0
	v_max_f32_e32 v9, 0x219392ef, v9
	s_and_b64 vcc, exec, s[4:5]
	s_mov_b64 s[0:1], -1
	v_mul_f32_e32 v10, 0xbfb8aa3b, v11
	v_exp_f32_e32 v10, v10
	s_nop 0
	v_add_f32_e32 v10, 1.0, v10
	v_rcp_f32_e32 v10, v10
	s_nop 0
	v_max_f32_e32 v10, 0x219392ef, v10
	v_cvt_pk_bf16_f32 v13, v13, v14
	v_cvt_pk_bf16_f32 v14, v15, v8
	v_add_co_u32_e32 v8, vcc, 0xb0000, v120
	v_cvt_pk_bf16_f32 v12, v16, v12
	v_cvt_pk_bf16_f32 v15, v9, v10
	v_addc_co_u32_e32 v9, vcc, 0, v121, vcc
	v_permlane16_swap_b32_e32 v12, v14
	v_permlane16_swap_b32_e32 v13, v15
	s_and_b64 vcc, exec, s[4:5]
	s_mov_b64 s[0:1], -1
	global_store_dwordx4 v[8:9], v[12:15], off
	v_mul_f32_e32 v8, 0xbfb8aa3b, v4
	v_exp_f32_e32 v8, v8
	s_nop 0
	v_add_f32_e32 v8, 1.0, v8
	v_rcp_f32_e32 v8, v8
	s_nop 0
	v_max_f32_e32 v8, 0x219392ef, v8
	s_and_b64 vcc, exec, s[4:5]
	s_mov_b64 s[0:1], -1
	v_mul_f32_e32 v4, 0xbfb8aa3b, v5
	v_exp_f32_e32 v4, v4
	s_nop 0
	v_add_f32_e32 v4, 1.0, v4
	v_rcp_f32_e32 v4, v4
	s_nop 0
	v_max_f32_e32 v4, 0x219392ef, v4
	s_and_b64 vcc, exec, s[4:5]
	s_mov_b64 s[0:1], -1
	v_mul_f32_e32 v5, 0xbfb8aa3b, v6
	v_exp_f32_e32 v5, v5
	s_nop 0
	v_add_f32_e32 v5, 1.0, v5
	v_rcp_f32_e32 v5, v5
	s_nop 0
	v_max_f32_e32 v5, 0x219392ef, v5
	s_and_b64 vcc, exec, s[4:5]
	s_mov_b64 s[0:1], -1
	v_mul_f32_e32 v6, 0xbfb8aa3b, v7
	v_exp_f32_e32 v6, v6
	s_nop 0
	v_add_f32_e32 v6, 1.0, v6
	v_rcp_f32_e32 v6, v6
	s_nop 0
	v_max_f32_e32 v6, 0x219392ef, v6
	s_and_b64 vcc, exec, s[4:5]
	s_mov_b64 s[0:1], -1
	v_mul_f32_e32 v7, 0xbfb8aa3b, v0
	v_exp_f32_e32 v7, v7
	s_nop 0
	v_add_f32_e32 v7, 1.0, v7
	v_rcp_f32_e32 v7, v7
	s_nop 0
	v_max_f32_e32 v7, 0x219392ef, v7
	s_and_b64 vcc, exec, s[4:5]
	s_mov_b64 s[0:1], -1
	v_mul_f32_e32 v0, 0xbfb8aa3b, v1
	v_exp_f32_e32 v0, v0
	s_nop 0
	v_add_f32_e32 v0, 1.0, v0
	v_rcp_f32_e32 v0, v0
	s_nop 0
	v_max_f32_e32 v0, 0x219392ef, v0
	s_and_b64 vcc, exec, s[4:5]
	s_mov_b64 s[0:1], -1
	v_mul_f32_e32 v1, 0xbfb8aa3b, v2
	v_exp_f32_e32 v1, v1
	s_nop 0
	v_add_f32_e32 v1, 1.0, v1
	v_rcp_f32_e32 v1, v1
	s_nop 0
	v_max_f32_e32 v1, 0x219392ef, v1
	s_and_b64 vcc, exec, s[4:5]
	s_mov_b64 s[0:1], -1
	v_mul_f32_e32 v2, 0xbfb8aa3b, v3
	v_exp_f32_e32 v2, v2
	s_nop 0
	v_add_f32_e32 v2, 1.0, v2
	v_rcp_f32_e32 v2, v2
	s_nop 0
	v_max_f32_e32 v2, 0x219392ef, v2
	s_branch .LBB0_143

; __device__ void phase1a(const Params& p) {
;     ...
;     u16* out = seg < 3 ? (u16*)(p.ws + OFF_Q + (size_t)seg * SZ_ACT) : (seg == 3 ? sg_sb : (u16*)(p.ws + OFF_SGSSD));
;     float sc = seg == 0 ? 0.08838834764831845f : 1.f;
;     gemm_tile_rt(h1, W1T, brow, btrow, out, DM, c0, sc, mode, nullptr, first, nbrow, nbtrow, has_next);
.LBB0_442:
	s_cmp_eq_u32 s0, 3
	s_cselect_b32 s23, s61, s63
	s_cselect_b32 s22, s60, s62
	s_cbranch_execz .LBB0_151
	s_branch .LBB0_152
.LBB0_684:
	v_mov_b32_e32 v0, 0
	global_load_dwordx2 v[2:3], v0, s[50:51] offset:160

; __device__ void phase2c(const Params& p) {
;   const int tid = tid_();
;   u16* y = (u16*)(p.ws + OFF_Z);
;   const float* ssq = (const float*)(p.ws + OFF_SSQP);
;   const int total = MTOK * 512;
;   for (int i = blockIdx.x * NT + tid; i < total; i += gridDim.x * NT) {
;     int t = i >> 9, c8 = i & 511, g = c8 >> 6;
;     float part = ssq[(size_t)t * 128 + g * 16 + (tid & 15)];
;     float tot = row16_sum(part);
;     float sc = rsqrtf(tot * (1.f / 512.f) + EPS);
;     i32x4 v = *(const i32x4*)(y + (size_t)t * 4096 + c8 * 8);
;     float4 w0 = *(const float4*)(p.ssd_norm + c8 * 8), w1 = *(const float4*)(p.ssd_norm + c8 * 8 + 4);
.LBB0_1180:
	s_or_b64 exec, exec, s[0:1]
	v_mov_b32_e32 v1, 0
	s_waitcnt lgkmcnt(0)
	s_barrier
	global_load_dwordx2 v[2:3], v1, s[50:51] offset:64
	global_load_dwordx2 v[6:7], v1, s[50:51] offset:112
	global_load_dwordx2 v[8:9], v1, s[50:51] offset:136
	global_load_dwordx2 v[10:11], v1, s[50:51] offset:160
	v_mov_b32_e32 v0, v214
	v_readlane_b32 s0, v254, 0
	s_mov_b32 s17, 0x800000
	s_waitcnt vmcnt(0)
	v_readfirstlane_b32 s5, v3
	v_add_u32_e32 v4, s0, v0
	v_readfirstlane_b32 s4, v2
	v_readfirstlane_b32 s3, v7
	v_readfirstlane_b32 s16, v6
	v_readfirstlane_b32 s14, v9
	v_readfirstlane_b32 s15, v8
	v_readfirstlane_b32 s1, v11
	v_readfirstlane_b32 s0, v10
	v_cmp_gt_i32_e32 vcc, s17, v4
	s_and_saveexec_b64 s[6:7], vcc
	s_cbranch_execz .LBB0_1183
	s_add_u32 s8, s0, 0xb100000
	s_addc_u32 s9, s1, 0
	s_add_u32 s10, s0, 0x4200000
	v_and_b32_e32 v2, 15, v0
	v_lshlrev_b32_e32 v0, 3, v0
	s_addc_u32 s11, s1, 0
	s_lshl_b32 s18, s33, 9
	v_lshl_add_u32 v5, s2, 12, v0
	s_lshl_b32 s19, s33, 12
	s_mov_b64 s[12:13], 0
	v_lshlrev_b32_e32 v2, 2, v2
	v_mov_b32_e32 v3, v1
	v_mov_b32_e32 v6, 0x358637bd
	s_mov_b32 s20, 0x7fffff
	v_and_b32_e32 v100, 0xff8, v5
	v_and_b32_e32 v103, 0x1c0, v4
	v_lshlrev_b32_e32 v101, 1, v100
	v_lshlrev_b32_e32 v102, 2, v100
	v_add_u32_e32 v103, v103, v2
	global_load_dwordx4 v[104:107], v102, s[4:5]
	global_load_dwordx4 v[108:111], v102, s[4:5] offset:16
	s_lshl_b32 s21, s33, 13
	s_lshl_b32 s22, s33, 9
	s_lshl_b32 s24, s18, 2
	s_lshl_b32 s25, s19, 2
	s_mov_b32 s26, s2
	s_mul_i32 s27, s33, 3
	s_lshl_b32 s31, s33, 2
; __device__ void phase2c(const Params& p) {
;     ...
;   for (int i = blockIdx.x * NT + tid; i < total; i += gridDim.x * NT) {
;     int t = i >> 9, c8 = i & 511, g = c8 >> 6;
;     float part = ssq[(size_t)t * 128 + g * 16 + (tid & 15)];
;     float tot = row16_sum(part);
;     float sc = rsqrtf(tot * (1.f / 512.f) + EPS);
;     i32x4 v = *(const i32x4*)(y + (size_t)t * 4096 + c8 * 8);
;     float4 w0 = *(const float4*)(p.ssd_norm + c8 * 8), w1 = *(const float4*)(p.ssd_norm + c8 * 8 + 4);
;     float wv[8] = {w0.x, w0.y, w0.z, w0.w, w1.x, w1.y, w1.z, w1.w};
;     i32x4 o;
; #pragma unroll
;     for (int e = 0; e < 4; ++e) {
;       unsigned u = (unsigned)v[e];
;       float a = __uint_as_float(u << 16) * sc * wv[2 * e], bq = __uint_as_float(u & 0xffff0000u) * sc * wv[2 * e + 1];
;       o[e] = (int)pack2(a, bq);
;     }
;     *(i32x4*)(y + (size_t)t * 4096 + c8 * 8) = o;
;   }
.Lp2c_loop:
	s_add_u32 s28, s26, s27
	s_cmp_lt_u32 s28, 0x4000
	s_cbranch_scc0 .Lp2c_done
	s_lshl_b32 s29, s26, 13
	s_lshl_b32 s30, s26, 9
	v_add_u32_e32 v113, s29, v101
	v_add_u32_e32 v96, s30, v103
	s_add_u32 s29, s29, s21
	s_add_u32 s30, s30, s22
	v_add_u32_e32 v114, s29, v101
	v_add_u32_e32 v97, s30, v103
	s_add_u32 s29, s29, s21
	s_add_u32 s30, s30, s22
	v_add_u32_e32 v115, s29, v101
	v_add_u32_e32 v98, s30, v103
	s_add_u32 s29, s29, s21
	s_add_u32 s30, s30, s22
	v_add_u32_e32 v116, s29, v101
	v_add_u32_e32 v99, s30, v103
	global_load_dword v120, v96, s[10:11]
	global_load_dword v122, v97, s[10:11]
	global_load_dword v124, v98, s[10:11]
	global_load_dword v126, v99, s[10:11]
	global_load_dwordx4 v[128:131], v113, s[8:9]
	global_load_dwordx4 v[132:135], v114, s[8:9]
	global_load_dwordx4 v[136:139], v115, s[8:9]
	global_load_dwordx4 v[140:143], v116, s[8:9]
	s_waitcnt vmcnt(4)
	v_add_f32_dpp v120, v120, v120 quad_perm:[1,0,3,2] row_mask:0xf bank_mask:0xf bound_ctrl:1
	v_add_f32_dpp v122, v122, v122 quad_perm:[1,0,3,2] row_mask:0xf bank_mask:0xf bound_ctrl:1
	v_add_f32_dpp v124, v124, v124 quad_perm:[1,0,3,2] row_mask:0xf bank_mask:0xf bound_ctrl:1
	v_add_f32_dpp v126, v126, v126 quad_perm:[1,0,3,2] row_mask:0xf bank_mask:0xf bound_ctrl:1
	v_add_f32_dpp v120, v120, v120 quad_perm:[2,3,0,1] row_mask:0xf bank_mask:0xf bound_ctrl:1
	v_add_f32_dpp v122, v122, v122 quad_perm:[2,3,0,1] row_mask:0xf bank_mask:0xf bound_ctrl:1
	v_add_f32_dpp v124, v124, v124 quad_perm:[2,3,0,1] row_mask:0xf bank_mask:0xf bound_ctrl:1
	v_add_f32_dpp v126, v126, v126 quad_perm:[2,3,0,1] row_mask:0xf bank_mask:0xf bound_ctrl:1
	v_add_f32_dpp v120, v120, v120 row_half_mirror row_mask:0xf bank_mask:0xf bound_ctrl:1
	v_add_f32_dpp v122, v122, v122 row_half_mirror row_mask:0xf bank_mask:0xf bound_ctrl:1
	v_add_f32_dpp v124, v124, v124 row_half_mirror row_mask:0xf bank_mask:0xf bound_ctrl:1
	v_add_f32_dpp v126, v126, v126 row_half_mirror row_mask:0xf bank_mask:0xf bound_ctrl:1
	v_add_f32_dpp v120, v120, v120 row_mirror row_mask:0xf bank_mask:0xf bound_ctrl:1
	v_add_f32_dpp v122, v122, v122 row_mirror row_mask:0xf bank_mask:0xf bound_ctrl:1
	v_add_f32_dpp v124, v124, v124 row_mirror row_mask:0xf bank_mask:0xf bound_ctrl:1
	v_add_f32_dpp v126, v126, v126 row_mirror row_mask:0xf bank_mask:0xf bound_ctrl:1
	v_fmamk_f32 v120, v120, 0x3b000000, v6
	v_fmamk_f32 v122, v122, 0x3b000000, v6
	v_fmamk_f32 v124, v124, 0x3b000000, v6
	v_fmamk_f32 v126, v126, 0x3b000000, v6
	v_rsq_f32_e32 v120, v120
	v_rsq_f32_e32 v122, v122
	v_rsq_f32_e32 v124, v124
	v_rsq_f32_e32 v126, v126
	s_nop 0
	s_waitcnt vmcnt(3)
	v_lshlrev_b32_e32 v144, 16, v128
	v_and_b32_e32 v145, 0xffff0000, v128
	v_lshlrev_b32_e32 v146, 16, v129
	v_and_b32_e32 v147, 0xffff0000, v129
	v_lshlrev_b32_e32 v148, 16, v130
	v_and_b32_e32 v149, 0xffff0000, v130
	v_lshlrev_b32_e32 v150, 16, v131
	v_and_b32_e32 v151, 0xffff0000, v131
	v_pk_mul_f32 v[144:145], v[120:121], v[144:145] op_sel_hi:[0,1]
	v_pk_mul_f32 v[146:147], v[120:121], v[146:147] op_sel_hi:[0,1]
	v_pk_mul_f32 v[148:149], v[120:121], v[148:149] op_sel_hi:[0,1]
	v_pk_mul_f32 v[150:151], v[120:121], v[150:151] op_sel_hi:[0,1]
	v_pk_mul_f32 v[144:145], v[104:105], v[144:145]
	v_pk_mul_f32 v[146:147], v[106:107], v[146:147]
	v_pk_mul_f32 v[148:149], v[108:109], v[148:149]
	v_pk_mul_f32 v[150:151], v[110:111], v[150:151]
	v_cvt_pk_bf16_f32 v176, v144, v145
	v_cvt_pk_bf16_f32 v177, v146, v147
	v_cvt_pk_bf16_f32 v178, v148, v149
	v_cvt_pk_bf16_f32 v179, v150, v151
	global_store_dwordx4 v113, v[176:179], s[8:9]
	s_waitcnt vmcnt(3)
	v_lshlrev_b32_e32 v152, 16, v132
	v_and_b32_e32 v153, 0xffff0000, v132
	v_lshlrev_b32_e32 v154, 16, v133
	v_and_b32_e32 v155, 0xffff0000, v133
	v_lshlrev_b32_e32 v156, 16, v134
	v_and_b32_e32 v157, 0xffff0000, v134
	v_lshlrev_b32_e32 v158, 16, v135
	v_and_b32_e32 v159, 0xffff0000, v135
	v_pk_mul_f32 v[152:153], v[122:123], v[152:153] op_sel_hi:[0,1]
	v_pk_mul_f32 v[154:155], v[122:123], v[154:155] op_sel_hi:[0,1]
	v_pk_mul_f32 v[156:157], v[122:123], v[156:157] op_sel_hi:[0,1]
	v_pk_mul_f32 v[158:159], v[122:123], v[158:159] op_sel_hi:[0,1]
	v_pk_mul_f32 v[152:153], v[104:105], v[152:153]
	v_pk_mul_f32 v[154:155], v[106:107], v[154:155]
	v_pk_mul_f32 v[156:157], v[108:109], v[156:157]
	v_pk_mul_f32 v[158:159], v[110:111], v[158:159]
	v_cvt_pk_bf16_f32 v180, v152, v153
	v_cvt_pk_bf16_f32 v181, v154, v155
	v_cvt_pk_bf16_f32 v182, v156, v157
	v_cvt_pk_bf16_f32 v183, v158, v159
	global_store_dwordx4 v114, v[180:183], s[8:9]
	s_waitcnt vmcnt(3)
	v_lshlrev_b32_e32 v160, 16, v136
	v_and_b32_e32 v161, 0xffff0000, v136
	v_lshlrev_b32_e32 v162, 16, v137
	v_and_b32_e32 v163, 0xffff0000, v137
	v_lshlrev_b32_e32 v164, 16, v138
	v_and_b32_e32 v165, 0xffff0000, v138
	v_lshlrev_b32_e32 v166, 16, v139
	v_and_b32_e32 v167, 0xffff0000, v139
	v_pk_mul_f32 v[160:161], v[124:125], v[160:161] op_sel_hi:[0,1]
	v_pk_mul_f32 v[162:163], v[124:125], v[162:163] op_sel_hi:[0,1]
	v_pk_mul_f32 v[164:165], v[124:125], v[164:165] op_sel_hi:[0,1]
	v_pk_mul_f32 v[166:167], v[124:125], v[166:167] op_sel_hi:[0,1]
	v_pk_mul_f32 v[160:161], v[104:105], v[160:161]
	v_pk_mul_f32 v[162:163], v[106:107], v[162:163]
	v_pk_mul_f32 v[164:165], v[108:109], v[164:165]
	v_pk_mul_f32 v[166:167], v[110:111], v[166:167]
	v_cvt_pk_bf16_f32 v184, v160, v161
	v_cvt_pk_bf16_f32 v185, v162, v163
	v_cvt_pk_bf16_f32 v186, v164, v165
	v_cvt_pk_bf16_f32 v187, v166, v167
	global_store_dwordx4 v115, v[184:187], s[8:9]
	s_waitcnt vmcnt(3)
	v_lshlrev_b32_e32 v168, 16, v140
	v_and_b32_e32 v169, 0xffff0000, v140
	v_lshlrev_b32_e32 v170, 16, v141
	v_and_b32_e32 v171, 0xffff0000, v141
	v_lshlrev_b32_e32 v172, 16, v142
	v_and_b32_e32 v173, 0xffff0000, v142
	v_lshlrev_b32_e32 v174, 16, v143
	v_and_b32_e32 v175, 0xffff0000, v143
	v_pk_mul_f32 v[168:169], v[126:127], v[168:169] op_sel_hi:[0,1]
	v_pk_mul_f32 v[170:171], v[126:127], v[170:171] op_sel_hi:[0,1]
	v_pk_mul_f32 v[172:173], v[126:127], v[172:173] op_sel_hi:[0,1]
	v_pk_mul_f32 v[174:175], v[126:127], v[174:175] op_sel_hi:[0,1]
	v_pk_mul_f32 v[168:169], v[104:105], v[168:169]
	v_pk_mul_f32 v[170:171], v[106:107], v[170:171]
	v_pk_mul_f32 v[172:173], v[108:109], v[172:173]
	v_pk_mul_f32 v[174:175], v[110:111], v[174:175]
	v_cvt_pk_bf16_f32 v188, v168, v169
	v_cvt_pk_bf16_f32 v189, v170, v171
	v_cvt_pk_bf16_f32 v190, v172, v173
	v_cvt_pk_bf16_f32 v191, v174, v175
	global_store_dwordx4 v116, v[188:191], s[8:9]
	s_add_u32 s26, s26, s31
	v_add_u32_e32 v4, s24, v4
	v_add_u32_e32 v5, s25, v5
	s_branch .Lp2c_loop
.Lp2c_done:
	v_cmp_gt_i32_e32 vcc, s17, v4
	s_and_b64 exec, exec, vcc
	s_cbranch_execz .LBB0_1183
